# speedup vs baseline: 1.0292x; 1.0012x over previous
; #define LAS __attribute__((address_space(3)))
; __device__ __forceinline__ unsigned pk_bf16(float lo, float hi) { f32x2 v = {lo, hi}; bf16x2_t b = __builtin_convertvector(v, bf16x2_t); return __builtin_bit_cast(unsigned, b); }
; __device__ __forceinline__ float bf_lo(unsigned w) { return __uint_as_float(w << 16); }
; __device__ __forceinline__ float bf_hi(unsigned w) { return __uint_as_float(w & 0xffff0000u); }
; __device__ __forceinline__ float wave_sum(float v) {
; #pragma unroll
;     for (int o = 1; o < 64; o <<= 1) v += __shfl_xor(v, o);
;     return v;
; }
; __device__ __forceinline__ void gmlp_unit(LAS unsigned char* lds, const bf16_t* __restrict__ Zb, const bf16_t* __restrict__ wsp, const float* __restrict__ bsp, bf16_t* __restrict__ mix, int chunk, int g) {
;     ...
;     for (int rr = 0; rr < 16; ++rr) {
;         const int q = wid * 16 + rr;
;         const unsigned w = *((const unsigned*)(Zb + (row0 + q) * NIN0 + 1088 + 1024 + g * 128) + lane);
;         const float a = bf_lo(w), c = bf_hi(w);
;         const float mean = wave_sum(a + c) * (1.0f / 128.0f), da = a - mean, dc = c - mean;
;         const float rstd = 1.0f / sqrtf(wave_sum(da * da + dc * dc) * (1.0f / 128.0f) + EPS);
;         *(LAS unsigned*)(lds + q * VS + lane * 4) = pk_bf16(da * rstd, dc * rstd);
;     }
.LBB0_617:
	v_readfirstlane_b32 s26, v165
	s_and_b32 s0, s55, 7
	s_ashr_i32 s38, s44, 3
	s_lshr_b32 s9, s26, 6
	s_lshl_b32 s0, s0, 8
	s_ashr_i32 s39, s38, 31
	s_mul_i32 s1, s9, 0x1400
	s_mul_i32 s2, s38, 0xd0000
	s_mul_i32 s4, s9, 0x1a000
	v_add_u32_e32 v4, s1, v94
	s_mul_hi_i32 s1, s38, 0xd0000
	s_mul_hi_u32 s3, s9, 0x1a000
	s_add_u32 s2, s2, s4
	s_addc_u32 s1, s1, s3
	s_or_b32 s0, s2, s0
	v_lshl_add_u64 v[0:1], v[50:51], 0, s[0:1]
	s_mov_b64 s[40:41], 0
	v_lshl_add_u64 v[136:137], v[0:1], 0, s[40:41]
	v_add_co_u32_e32 v138, vcc, 0x10701000, v136
	s_nop 1
	v_addc_co_u32_e32 v139, vcc, 0, v137, vcc
	v_add_co_u32_e32 v140, vcc, s59, v136
	s_nop 1
	v_addc_co_u32_e32 v141, vcc, 0, v137, vcc
	v_add_co_u32_e32 v142, vcc, s62, v136
	s_nop 1
	v_addc_co_u32_e32 v143, vcc, 0, v137, vcc
	v_add_co_u32_e32 v144, vcc, s63, v136
	s_nop 1
	v_addc_co_u32_e32 v145, vcc, 0, v137, vcc
	global_load_dword v146, v[138:139], off offset:128
	global_load_dword v147, v[140:141], off offset:2688
	global_load_dword v148, v[142:143], off offset:1152
	global_load_dword v149, v[144:145], off offset:3712
.LBB0_618:
	s_waitcnt vmcnt(0)
	v_lshlrev_b32_e32 v2, 16, v146
	v_and_b32_e32 v3, 0xffff0000, v146
	v_lshlrev_b32_e32 v6, 16, v147
	v_and_b32_e32 v7, 0xffff0000, v147
	v_lshlrev_b32_e32 v8, 16, v148
	v_and_b32_e32 v9, 0xffff0000, v148
	v_lshlrev_b32_e32 v10, 16, v149
	v_and_b32_e32 v11, 0xffff0000, v149
	s_add_u32 s40, s40, 0x6800
	s_addc_u32 s41, s41, 0
	s_cmp_lg_u32 s40, 0x1a000
	s_cbranch_scc0 .Lgm_nopf
	v_lshl_add_u64 v[136:137], v[0:1], 0, s[40:41]
	v_add_co_u32_e32 v138, vcc, 0x10701000, v136
	s_nop 1
	v_addc_co_u32_e32 v139, vcc, 0, v137, vcc
	v_add_co_u32_e32 v140, vcc, s59, v136
	s_nop 1
	v_addc_co_u32_e32 v141, vcc, 0, v137, vcc
	v_add_co_u32_e32 v142, vcc, s62, v136
	s_nop 1
	v_addc_co_u32_e32 v143, vcc, 0, v137, vcc
	v_add_co_u32_e32 v144, vcc, s63, v136
	s_nop 1
	v_addc_co_u32_e32 v145, vcc, 0, v137, vcc
	global_load_dword v146, v[138:139], off offset:128
	global_load_dword v147, v[140:141], off offset:2688
	global_load_dword v148, v[142:143], off offset:1152
	global_load_dword v149, v[144:145], off offset:3712
.Lgm_nopf:
	s_cmp_lg_u32 s40, 0x1a000
	v_add_f32_e32 v5, v3, v2
	v_add_f32_e32 v12, v7, v6
	v_add_f32_e32 v13, v9, v8
	v_add_f32_e32 v14, v11, v10
	v_add_f32_dpp v5, v5, v5 quad_perm:[1,0,3,2] row_mask:0xf bank_mask:0xf
	v_add_f32_dpp v12, v12, v12 quad_perm:[1,0,3,2] row_mask:0xf bank_mask:0xf
	v_add_f32_dpp v13, v13, v13 quad_perm:[1,0,3,2] row_mask:0xf bank_mask:0xf
	v_add_f32_dpp v14, v14, v14 quad_perm:[1,0,3,2] row_mask:0xf bank_mask:0xf
	v_add_f32_dpp v5, v5, v5 quad_perm:[2,3,0,1] row_mask:0xf bank_mask:0xf
	v_add_f32_dpp v12, v12, v12 quad_perm:[2,3,0,1] row_mask:0xf bank_mask:0xf
	v_add_f32_dpp v13, v13, v13 quad_perm:[2,3,0,1] row_mask:0xf bank_mask:0xf
	v_add_f32_dpp v14, v14, v14 quad_perm:[2,3,0,1] row_mask:0xf bank_mask:0xf
	v_add_f32_dpp v5, v5, v5 row_half_mirror row_mask:0xf bank_mask:0xf
	v_add_f32_dpp v12, v12, v12 row_half_mirror row_mask:0xf bank_mask:0xf
	v_add_f32_dpp v13, v13, v13 row_half_mirror row_mask:0xf bank_mask:0xf
	v_add_f32_dpp v14, v14, v14 row_half_mirror row_mask:0xf bank_mask:0xf
	v_add_f32_dpp v5, v5, v5 row_mirror row_mask:0xf bank_mask:0xf
	v_add_f32_dpp v12, v12, v12 row_mirror row_mask:0xf bank_mask:0xf
	v_add_f32_dpp v13, v13, v13 row_mirror row_mask:0xf bank_mask:0xf
	v_add_f32_dpp v14, v14, v14 row_mirror row_mask:0xf bank_mask:0xf
	v_mov_b32_e32 v15, v5
	v_mov_b32_e32 v16, v12
	v_mov_b32_e32 v17, v13
	v_mov_b32_e32 v18, v14
	v_permlane16_swap_b32_e32 v5, v15
	v_permlane16_swap_b32_e32 v12, v16
	v_permlane16_swap_b32_e32 v13, v17
	v_permlane16_swap_b32_e32 v14, v18
	v_add_f32_e32 v5, v5, v15
	v_add_f32_e32 v12, v12, v16
	v_add_f32_e32 v13, v13, v17
	v_add_f32_e32 v14, v14, v18
	v_mov_b32_e32 v15, v5
	v_mov_b32_e32 v16, v12
	v_mov_b32_e32 v17, v13
	v_mov_b32_e32 v18, v14
	v_permlane32_swap_b32_e32 v5, v15
	v_permlane32_swap_b32_e32 v12, v16
	v_permlane32_swap_b32_e32 v13, v17
	v_permlane32_swap_b32_e32 v14, v18
	v_add_f32_e32 v5, v5, v15
	v_add_f32_e32 v15, v12, v16
	v_add_f32_e32 v13, v13, v17
	v_add_f32_e32 v17, v14, v18
	v_mul_f32_e32 v12, 0x3c000000, v5
	v_mul_f32_e32 v14, 0x3c000000, v15
	v_mul_f32_e32 v16, 0x3c000000, v13
	v_pk_add_f32 v[2:3], v[2:3], v[12:13] op_sel_hi:[1,0] neg_lo:[0,1] neg_hi:[0,1]
	v_pk_add_f32 v[6:7], v[6:7], v[14:15] op_sel_hi:[1,0] neg_lo:[0,1] neg_hi:[0,1]
	v_pk_add_f32 v[8:9], v[8:9], v[16:17] op_sel_hi:[1,0] neg_lo:[0,1] neg_hi:[0,1]
	v_pk_mul_f32 v[12:13], v[2:3], v[2:3]
	v_mul_f32_e32 v18, 0x3c000000, v17
	v_pk_mul_f32 v[14:15], v[6:7], v[6:7]
	v_pk_mul_f32 v[16:17], v[8:9], v[8:9]
	v_add_f32_e32 v5, v12, v13
	v_add_f32_e32 v12, v14, v15
	v_add_f32_e32 v13, v16, v17
	v_pk_add_f32 v[10:11], v[10:11], v[18:19] op_sel_hi:[1,0] neg_lo:[0,1] neg_hi:[0,1]
	v_pk_mul_f32 v[18:19], v[10:11], v[10:11]
	v_add_f32_e32 v14, v18, v19
	v_add_f32_dpp v5, v5, v5 quad_perm:[1,0,3,2] row_mask:0xf bank_mask:0xf
	v_add_f32_dpp v12, v12, v12 quad_perm:[1,0,3,2] row_mask:0xf bank_mask:0xf
	v_add_f32_dpp v13, v13, v13 quad_perm:[1,0,3,2] row_mask:0xf bank_mask:0xf
	v_add_f32_dpp v14, v14, v14 quad_perm:[1,0,3,2] row_mask:0xf bank_mask:0xf
	v_add_f32_dpp v5, v5, v5 quad_perm:[2,3,0,1] row_mask:0xf bank_mask:0xf
	v_add_f32_dpp v12, v12, v12 quad_perm:[2,3,0,1] row_mask:0xf bank_mask:0xf
	v_add_f32_dpp v13, v13, v13 quad_perm:[2,3,0,1] row_mask:0xf bank_mask:0xf
	v_add_f32_dpp v14, v14, v14 quad_perm:[2,3,0,1] row_mask:0xf bank_mask:0xf
	v_add_f32_dpp v5, v5, v5 row_half_mirror row_mask:0xf bank_mask:0xf
	v_add_f32_dpp v12, v12, v12 row_half_mirror row_mask:0xf bank_mask:0xf
; #define LAS __attribute__((address_space(3)))
; __device__ __forceinline__ unsigned pk_bf16(float lo, float hi) { f32x2 v = {lo, hi}; bf16x2_t b = __builtin_convertvector(v, bf16x2_t); return __builtin_bit_cast(unsigned, b); }
; __device__ __forceinline__ float wave_sum(float v) {
; #pragma unroll
;     for (int o = 1; o < 64; o <<= 1) v += __shfl_xor(v, o);
;     return v;
; }
; __device__ __forceinline__ void gmlp_unit(LAS unsigned char* lds, const bf16_t* __restrict__ Zb, const bf16_t* __restrict__ wsp, const float* __restrict__ bsp, bf16_t* __restrict__ mix, int chunk, int g) {
;     ...
;         const float mean = wave_sum(a + c) * (1.0f / 128.0f), da = a - mean, dc = c - mean;
;         const float rstd = 1.0f / sqrtf(wave_sum(da * da + dc * dc) * (1.0f / 128.0f) + EPS);
;         *(LAS unsigned*)(lds + q * VS + lane * 4) = pk_bf16(da * rstd, dc * rstd);
;     }
	v_add_f32_dpp v13, v13, v13 row_half_mirror row_mask:0xf bank_mask:0xf
	v_add_f32_dpp v14, v14, v14 row_half_mirror row_mask:0xf bank_mask:0xf
	v_add_f32_dpp v5, v5, v5 row_mirror row_mask:0xf bank_mask:0xf
	v_add_f32_dpp v12, v12, v12 row_mirror row_mask:0xf bank_mask:0xf
	v_add_f32_dpp v13, v13, v13 row_mirror row_mask:0xf bank_mask:0xf
	v_add_f32_dpp v14, v14, v14 row_mirror row_mask:0xf bank_mask:0xf
	v_mov_b32_e32 v15, v5
	v_mov_b32_e32 v16, v12
	v_mov_b32_e32 v17, v13
	v_mov_b32_e32 v18, v14
	v_permlane16_swap_b32_e32 v5, v15
	v_permlane16_swap_b32_e32 v12, v16
	v_permlane16_swap_b32_e32 v13, v17
	v_permlane16_swap_b32_e32 v14, v18
	v_add_f32_e32 v5, v5, v15
	v_add_f32_e32 v12, v12, v16
	v_add_f32_e32 v13, v13, v17
	v_add_f32_e32 v14, v14, v18
	v_mov_b32_e32 v15, v5
	v_mov_b32_e32 v16, v12
	v_mov_b32_e32 v17, v13
	v_mov_b32_e32 v18, v14
	v_permlane32_swap_b32_e32 v5, v15
	v_permlane32_swap_b32_e32 v12, v16
	v_permlane32_swap_b32_e32 v13, v17
	v_permlane32_swap_b32_e32 v14, v18
	v_add_f32_e32 v5, v5, v15
	v_add_f32_e32 v12, v12, v16
	v_add_f32_e32 v13, v13, v17
	v_add_f32_e32 v14, v14, v18
	v_fmamk_f32 v5, v5, 0x3c000000, v95
	v_fmamk_f32 v12, v12, 0x3c000000, v95
	v_fmamk_f32 v13, v13, 0x3c000000, v95
	v_mul_f32_e32 v15, 0x4f800000, v5
	v_cmp_gt_f32_e64 s[4:5], s58, v5
	v_mul_f32_e32 v16, 0x4f800000, v12
	v_cmp_gt_f32_e32 vcc, s58, v12
	v_mul_f32_e32 v17, 0x4f800000, v13
	v_cmp_gt_f32_e64 s[0:1], s58, v13
	v_cndmask_b32_e64 v5, v5, v15, s[4:5]
	v_cndmask_b32_e32 v12, v12, v16, vcc
	v_cndmask_b32_e64 v13, v13, v17, s[0:1]
	v_sqrt_f32_e32 v15, v5
	v_fmamk_f32 v14, v14, 0x3c000000, v95
	v_sqrt_f32_e32 v16, v12
	v_sqrt_f32_e32 v17, v13
	v_mul_f32_e32 v18, 0x4f800000, v14
	v_cmp_gt_f32_e64 s[2:3], s58, v14
	v_add_u32_e32 v19, -1, v15
	v_add_u32_e32 v20, 1, v15
	v_cndmask_b32_e64 v14, v14, v18, s[2:3]
	v_sqrt_f32_e32 v18, v14
	v_add_u32_e32 v21, -1, v16
	v_add_u32_e32 v23, -1, v17
	v_fma_f32 v27, -v19, v15, v5
	v_add_u32_e32 v22, 1, v16
	v_add_u32_e32 v24, 1, v17
	v_fma_f32 v28, -v20, v15, v5
	v_fma_f32 v29, -v21, v16, v12
	v_fma_f32 v31, -v23, v17, v13
	v_cmp_ge_f32_e64 s[10:11], 0, v27
	v_fma_f32 v30, -v22, v16, v12
	v_fma_f32 v32, -v24, v17, v13
	v_cndmask_b32_e64 v15, v15, v19, s[10:11]
	v_cmp_ge_f32_e64 s[10:11], 0, v29
	v_cmp_ge_f32_e64 s[12:13], 0, v31
	v_cmp_lt_f32_e64 s[16:17], 0, v28
	v_add_u32_e32 v25, -1, v18
	v_cndmask_b32_e64 v16, v16, v21, s[10:11]
	v_cmp_lt_f32_e64 s[10:11], 0, v30
	v_cndmask_b32_e64 v17, v17, v23, s[12:13]
	v_cmp_lt_f32_e64 s[12:13], 0, v32
	v_cndmask_b32_e64 v15, v15, v20, s[16:17]
	v_add_u32_e32 v26, 1, v18
	v_fma_f32 v33, -v25, v18, v14
	v_cndmask_b32_e64 v16, v16, v22, s[10:11]
	v_cndmask_b32_e64 v17, v17, v24, s[12:13]
	v_mul_f32_e32 v19, 0x37800000, v15
	v_fma_f32 v34, -v26, v18, v14
	v_cmp_ge_f32_e64 s[14:15], 0, v33
	v_mul_f32_e32 v20, 0x37800000, v16
	v_mul_f32_e32 v21, 0x37800000, v17
	v_cndmask_b32_e64 v15, v15, v19, s[4:5]
	v_cmp_class_f32_e64 s[4:5], v5, v96
	v_cndmask_b32_e64 v18, v18, v25, s[14:15]
	v_cmp_lt_f32_e64 s[14:15], 0, v34
	v_cndmask_b32_e32 v16, v16, v20, vcc
	v_cmp_class_f32_e32 vcc, v12, v96
	v_cndmask_b32_e64 v17, v17, v21, s[0:1]
	v_cmp_class_f32_e64 s[0:1], v13, v96
	v_cndmask_b32_e64 v5, v15, v5, s[4:5]
	v_cndmask_b32_e64 v18, v18, v26, s[14:15]
	v_cndmask_b32_e32 v15, v16, v12, vcc
	v_cndmask_b32_e64 v13, v17, v13, s[0:1]
	v_div_scale_f32 v12, s[0:1], v5, v5, 1.0
	v_mul_f32_e32 v22, 0x37800000, v18
	v_div_scale_f32 v17, s[0:1], v15, v15, 1.0
	v_rcp_f32_e32 v23, v12
	v_cndmask_b32_e64 v18, v18, v22, s[2:3]
	v_cmp_class_f32_e64 s[2:3], v14, v96
	v_rcp_f32_e32 v24, v17
	v_fma_f32 v27, -v12, v23, 1.0
	v_cndmask_b32_e64 v14, v18, v14, s[2:3]
	v_div_scale_f32 v19, s[2:3], v13, v13, 1.0
	v_div_scale_f32 v21, s[4:5], v14, v14, 1.0
	v_rcp_f32_e32 v25, v19
	v_rcp_f32_e32 v26, v21
	v_div_scale_f32 v16, vcc, 1.0, v5, 1.0
	v_fma_f32 v28, -v17, v24, 1.0
	v_fmac_f32_e32 v23, v27, v23
	v_div_scale_f32 v18, s[0:1], 1.0, v15, 1.0
	v_fmac_f32_e32 v24, v28, v24
	v_mul_f32_e32 v27, v16, v23
	v_fma_f32 v29, -v19, v25, 1.0
	v_mul_f32_e32 v28, v18, v24
	v_fma_f32 v31, -v12, v27, v16
	v_div_scale_f32 v20, s[2:3], 1.0, v13, 1.0
	v_fma_f32 v30, -v21, v26, 1.0
	v_fmac_f32_e32 v25, v29, v25
	v_fma_f32 v32, -v17, v28, v18
	v_fmac_f32_e32 v27, v31, v23
	v_div_scale_f32 v22, s[4:5], 1.0, v14, 1.0
	v_fmac_f32_e32 v26, v30, v26
	v_mul_f32_e32 v29, v20, v25
	v_fmac_f32_e32 v28, v32, v24
	v_fma_f32 v12, -v12, v27, v16
	v_mul_f32_e32 v30, v22, v26
	v_fma_f32 v33, -v19, v29, v20
	v_fma_f32 v16, -v17, v28, v18
	v_div_fmas_f32 v12, v12, v23, v27
	s_mov_b64 vcc, s[0:1]
	v_fma_f32 v34, -v21, v30, v22
	v_fmac_f32_e32 v29, v33, v25
	v_div_fixup_f32 v12, v12, v5, 1.0
	v_div_fmas_f32 v5, v16, v24, v28
	v_fmac_f32_e32 v30, v34, v26
	v_fma_f32 v17, -v19, v29, v20
	v_pk_mul_f32 v[2:3], v[2:3], v[12:13] op_sel_hi:[1,0]
	v_div_fixup_f32 v12, v5, v15, 1.0
	s_mov_b64 vcc, s[2:3]
	v_fma_f32 v18, -v21, v30, v22
	v_div_fmas_f32 v5, v17, v25, v29
	v_cvt_pk_bf16_f32 v15, v2, v3
	v_pk_mul_f32 v[2:3], v[6:7], v[12:13] op_sel_hi:[1,0]
	s_mov_b64 vcc, s[4:5]
	v_div_fixup_f32 v6, v5, v13, 1.0
	v_div_fmas_f32 v5, v18, v26, v30
	v_cvt_pk_bf16_f32 v7, v2, v3
	v_pk_mul_f32 v[2:3], v[8:9], v[6:7] op_sel_hi:[1,0]
	v_div_fixup_f32 v6, v5, v14, 1.0
	v_cvt_pk_bf16_f32 v5, v2, v3
	v_pk_mul_f32 v[2:3], v[10:11], v[6:7] op_sel_hi:[1,0]
	ds_write2_b32 v4, v15, v7 offset1:80
	v_cvt_pk_bf16_f32 v2, v2, v3
	ds_write2_b32 v4, v5, v2 offset0:160 offset1:240
	v_add_u32_e32 v4, 0x500, v4
	s_cbranch_scc1 .LBB0_618
; #define LAS __attribute__((address_space(3)))
; #define MFMA32(a, b, c) __builtin_amdgcn_mfma_f32_32x32x16_bf16((a), (b), (c), 0, 0, 0)
; __device__ __forceinline__ void gmlp_unit(LAS unsigned char* lds, const bf16_t* __restrict__ Zb, const bf16_t* __restrict__ wsp, const float* __restrict__ bsp, bf16_t* __restrict__ mix, int chunk, int g) {
;     ...
;     __syncthreads();
;     const int pb = wid >> 1, cb0 = 2 * (wid & 1);
;     f32x16 acc[2];
; #pragma unroll
;     for (int e = 0; e < 16; ++e) { acc[0][e] = 0.f; acc[1][e] = 0.f; }
;     const bf16_t* ap = wsp + (size_t)g * 16384 + (size_t)(32 * pb + r) * 128 + 8 * h;
;     const int vlane = (8 * h + ((lane & 15) >> 2)) * VS + (16 * ((lane >> 4) & 1) + 4 * (lane & 3)) * 2;
; #pragma unroll
;     for (int ks = 0; ks < 8; ++ks) {
;         const bf16x8 af = *(const bf16x8*)(ap + 16 * ks);
; #pragma unroll
;         for (int ci = 0; ci < 2; ++ci) {
;             const LAS unsigned char* vp = lds + vlane + (16 * ks) * VS + (cb0 + ci) * 64;
;             const s16x4 lo = tr_read(vp), hi = tr_read(vp + 4 * VS);
;             const bf16x8 vf = __builtin_shufflevector(lo, hi, 0, 1, 2, 3, 4, 5, 6, 7);
;             acc[ci] = MFMA32(af, vf, acc[ci]);
;         }
;     }
	s_and_b32 s2, s44, 7
	s_lshl_b64 s[0:1], s[38:39], 7
	s_lshl_b32 s3, s2, 15
	s_add_u32 s4, s45, s3
	s_addc_u32 s5, s54, 0
	s_lshr_b32 s3, s26, 2
	s_and_b32 s3, s3, 0x3fffffe0
	v_or_b32_e32 v48, s3, v166
	v_lshlrev_b64 v[0:1], 8, v[48:49]
	v_lshl_add_u64 v[0:1], s[4:5], 0, v[0:1]
	v_mov_b32_e32 v53, v49
	v_lshl_add_u64 v[58:59], v[0:1], 0, v[52:53]
	s_waitcnt lgkmcnt(0)
	s_barrier
	global_load_dwordx4 v[0:3], v[58:59], off
	global_load_dwordx4 v[40:43], v[58:59], off offset:32
	global_load_dwordx4 v[32:35], v[58:59], off offset:64
	global_load_dwordx4 v[36:39], v[58:59], off offset:96
	global_load_dwordx4 v[44:47], v[58:59], off offset:128
	s_lshl_b32 s4, s9, 7
	s_and_b32 s5, s4, 0x80
	v_add_u32_e32 v97, s5, v86
	ds_read_b64_tr_b16 v[4:5], v97
	ds_read_b64_tr_b16 v[6:7], v97 offset:1280
	global_load_dwordx4 v[62:65], v[58:59], off offset:160
	s_or_b32 s4, s5, 64
	v_add_u32_e32 v134, s4, v86
	ds_read_b64_tr_b16 v[60:61], v97 offset:37120
	v_or_b32_e32 v48, s3, v87
	v_mov_b32_e32 v85, v49
	v_mov_b32_e32 v123, v49
	v_mov_b32_e32 v125, v49
	v_mov_b32_e32 v129, v49
	v_lshl_add_u32 v84, s2, 7, v48
	v_or_b32_e32 v122, 1, v48
	v_or_b32_e32 v124, 2, v48
	v_or_b32_e32 v128, 8, v48
	v_mov_b64_e32 v[54:55], s[20:21]
	v_lshl_add_u64 v[132:133], s[0:1], 0, v[48:49]
	s_lshl_b32 s26, s2, 8
	v_lshlrev_b32_e32 v53, 1, v166
	v_mov_b32_e32 v57, v49
	v_or_b32_e32 v56, s5, v53
	v_mov_b32_e32 v127, v49
	v_or_b32_e32 v126, 3, v48
	v_mov_b32_e32 v131, v49
	v_or_b32_e32 v130, 9, v48
	s_waitcnt vmcnt(5) lgkmcnt(1)
	v_mfma_f32_32x32x16_bf16 v[16:31], v[0:3], v[4:7], 0
	ds_read_b64_tr_b16 v[4:5], v134
	ds_read_b64_tr_b16 v[6:7], v134 offset:1280
	ds_read_b64_tr_b16 v[82:83], v134 offset:37120
	ds_read_b64_tr_b16 v[66:67], v97 offset:5120
	ds_read_b64_tr_b16 v[68:69], v97 offset:6400
	ds_read_b64_tr_b16 v[70:71], v97 offset:10240
	ds_read_b64_tr_b16 v[72:73], v97 offset:11520
	global_load_dwordx4 v[98:101], v[58:59], off offset:192
	s_waitcnt lgkmcnt(5)
	v_mfma_f32_32x32x16_bf16 v[0:15], v[0:3], v[4:7], 0
	s_waitcnt vmcnt(5) lgkmcnt(2)
	v_mfma_f32_32x32x16_bf16 v[16:31], v[40:43], v[66:69], v[16:31]
	ds_read_b64_tr_b16 v[66:67], v134 offset:5120
	ds_read_b64_tr_b16 v[68:69], v134 offset:6400
	ds_read_b64_tr_b16 v[74:75], v134 offset:10240
	ds_read_b64_tr_b16 v[76:77], v134 offset:11520
	s_waitcnt lgkmcnt(2)
	v_mfma_f32_32x32x16_bf16 v[0:15], v[40:43], v[66:69], v[0:15]
	ds_read_b64_tr_b16 v[40:41], v97 offset:15360
	ds_read_b64_tr_b16 v[42:43], v97 offset:16640
	ds_read_b64_tr_b16 v[66:67], v97 offset:20480
	ds_read_b64_tr_b16 v[68:69], v97 offset:21760
	ds_read_b64_tr_b16 v[78:79], v97 offset:25600
	ds_read_b64_tr_b16 v[80:81], v97 offset:26880
	ds_read_b64_tr_b16 v[102:103], v97 offset:30720
	ds_read_b64_tr_b16 v[104:105], v97 offset:32000
	s_waitcnt vmcnt(4)
	v_mfma_f32_32x32x16_bf16 v[16:31], v[32:35], v[70:73], v[16:31]
	ds_read_b64_tr_b16 v[70:71], v134 offset:15360
	ds_read_b64_tr_b16 v[72:73], v134 offset:16640
	ds_read_b64_tr_b16 v[106:107], v134 offset:20480
	ds_read_b64_tr_b16 v[108:109], v134 offset:21760
	global_load_dwordx4 v[110:113], v[58:59], off offset:224
	ds_read_b64_tr_b16 v[114:115], v134 offset:25600
	ds_read_b64_tr_b16 v[116:117], v134 offset:26880
	ds_read_b64_tr_b16 v[118:119], v134 offset:30720
	ds_read_b64_tr_b16 v[120:121], v134 offset:32000
	s_waitcnt lgkmcnt(14)
	v_mfma_f32_32x32x16_bf16 v[0:15], v[32:35], v[74:77], v[0:15]
	v_mad_u64_u32 v[32:33], s[2:3], v132, s64, v[54:55]
	v_mad_i32_i24 v33, v133, s64, v33
	v_lshl_add_u64 v[74:75], v[32:33], 0, s[26:27]
	v_lshl_add_u64 v[32:33], v[74:75], 0, v[56:57]
	global_load_ushort v135, v[32:33], off offset:2176
	s_waitcnt vmcnt(5)
	v_mfma_f32_32x32x16_bf16 v[16:31], v[36:39], v[40:43], v[16:31]
	v_lshl_add_u64 v[40:41], v[84:85], 2, s[36:37]
	v_lshl_add_u64 v[42:43], s[0:1], 0, v[122:123]
	v_lshl_add_u64 v[84:85], s[0:1], 0, v[124:125]
	v_lshl_add_u64 v[124:125], s[0:1], 0, v[128:129]
	v_lshl_add_u64 v[122:123], s[0:1], 0, v[126:127]
	v_lshl_add_u64 v[126:127], s[0:1], 0, v[130:131]
	s_waitcnt lgkmcnt(6)
	v_mfma_f32_32x32x16_bf16 v[0:15], v[36:39], v[70:73], v[0:15]
	v_mad_u64_u32 v[36:37], s[2:3], v42, s64, v[54:55]
	v_mad_i32_i24 v37, v43, s64, v37
	v_lshl_add_u64 v[76:77], v[36:37], 0, s[26:27]
	v_lshl_add_u64 v[36:37], v[76:77], 0, v[56:57]
	global_load_ushort v128, v[36:37], off offset:2176
	s_waitcnt vmcnt(5)
	v_mfma_f32_32x32x16_bf16 v[16:31], v[44:47], v[66:69], v[16:31]
	s_waitcnt lgkmcnt(4)
	v_mfma_f32_32x32x16_bf16 v[0:15], v[44:47], v[106:109], v[0:15]
	v_mad_u64_u32 v[44:45], s[2:3], v124, s64, v[54:55]
	v_mad_i32_i24 v45, v125, s64, v45
	v_lshl_add_u64 v[68:69], v[44:45], 0, s[26:27]
	v_lshl_add_u64 v[44:45], v[68:69], 0, v[56:57]
	global_load_ushort v108, v[44:45], off offset:2176
	global_load_dwordx4 v[32:35], v[40:41], off
	v_mad_u64_u32 v[36:37], s[2:3], v84, s64, v[54:55]
	v_mad_i32_i24 v37, v85, s64, v37
	v_lshl_add_u64 v[72:73], v[36:37], 0, s[26:27]
	v_lshl_add_u64 v[36:37], v[72:73], 0, v[56:57]
	global_load_ushort v106, v[36:37], off offset:2176
	v_mad_u64_u32 v[36:37], s[2:3], v122, s64, v[54:55]
	v_mad_i32_i24 v37, v123, s64, v37
	v_lshl_add_u64 v[70:71], v[36:37], 0, s[26:27]
	s_waitcnt vmcnt(7)
	v_mfma_f32_32x32x16_bf16 v[16:31], v[62:65], v[78:81], v[16:31]
	v_lshl_add_u64 v[36:37], v[70:71], 0, v[56:57]
	global_load_ushort v107, v[36:37], off offset:2176
	v_mad_u64_u32 v[44:45], s[2:3], v126, s64, v[54:55]
	global_load_dwordx4 v[36:39], v[40:41], off offset:32
	v_mad_i32_i24 v45, v127, s64, v45
	v_lshl_add_u64 v[66:67], v[44:45], 0, s[26:27]
	v_lshl_add_u64 v[44:45], v[66:67], 0, v[56:57]
	s_waitcnt vmcnt(8)
; #define LAS __attribute__((address_space(3)))
; __device__ __forceinline__ float bf2f(bf16_t v) { return __uint_as_float((unsigned)v << 16); }
; __device__ __forceinline__ bf16_t f2bf(float f) { return (bf16_t)(pk_bf16(f, 0.f) & 0xffffu); }
; __device__ __forceinline__ int crow(int reg, int h) { return (reg & 3) + 8 * (reg >> 2) + 4 * h; }
; #define MFMA32(a, b, c) __builtin_amdgcn_mfma_f32_32x32x16_bf16((a), (b), (c), 0, 0, 0)
; __device__ __forceinline__ void gmlp_unit(LAS unsigned char* lds, const bf16_t* __restrict__ Zb, const bf16_t* __restrict__ wsp, const float* __restrict__ bsp, bf16_t* __restrict__ mix, int chunk, int g) {
;     ...
; #pragma unroll
;     for (int ks = 0; ks < 8; ++ks) {
;         const bf16x8 af = *(const bf16x8*)(ap + 16 * ks);
; #pragma unroll
;         for (int ci = 0; ci < 2; ++ci) {
;             const LAS unsigned char* vp = lds + vlane + (16 * ks) * VS + (cb0 + ci) * 64;
;             const s16x4 lo = tr_read(vp), hi = tr_read(vp + 4 * VS);
;             const bf16x8 vf = __builtin_shufflevector(lo, hi, 0, 1, 2, 3, 4, 5, 6, 7);
;             acc[ci] = MFMA32(af, vf, acc[ci]);
;         }
;     }
; #pragma unroll
;     for (int ci = 0; ci < 2; ++ci)
; #pragma unroll
;         for (int e = 0; e < 16; ++e) {
;             const int p = 32 * pb + crow(e, h), c = 32 * (cb0 + ci) + r;
;             const float u = bf2f(Zb[(row0 + p) * NIN0 + 1088 + g * 128 + c]);
;             mix[(row0 + p) * DM + 1024 + g * 128 + c] = f2bf(u * (acc[ci][e] + bsp[g * 128 + p]));
	v_mfma_f32_32x32x16_bf16 v[16:31], v[98:101], v[102:105], v[16:31]
	global_load_ushort v104, v[44:45], off offset:2176
	ds_read_b64_tr_b16 v[58:59], v97 offset:35840
	ds_read_b64_tr_b16 v[80:81], v134 offset:35840
	v_mov_b32_e32 v45, v49
	v_or_b32_e32 v44, 10, v48
	s_add_u32 s2, s78, s26
	s_addc_u32 s3, s79, 0
	v_mov_b32_e32 v47, v49
	s_waitcnt lgkmcnt(4)
	v_mfma_f32_32x32x16_bf16 v[0:15], v[62:65], v[114:117], v[0:15]
	v_or_b32_e32 v46, 11, v48
	v_lshl_add_u64 v[62:63], s[2:3], 0, v[56:57]
	v_lshlrev_b64 v[64:65], 12, v[42:43]
	s_add_i32 s44, s44, s28
	s_add_i32 s55, s55, s28
	s_cmpk_lt_i32 s44, 0x480
	s_waitcnt lgkmcnt(2)
	v_mfma_f32_32x32x16_bf16 v[0:15], v[98:101], v[118:121], v[0:15]
	v_lshl_add_u64 v[98:99], s[0:1], 0, v[44:45]
	v_mad_u64_u32 v[44:45], s[6:7], v98, s64, v[54:55]
	v_mad_i32_i24 v45, v99, s64, v45
	v_lshl_add_u64 v[78:79], v[44:45], 0, s[26:27]
	v_lshl_add_u64 v[44:45], v[78:79], 0, v[56:57]
	global_load_ushort v97, v[44:45], off offset:2176
	s_waitcnt vmcnt(9) lgkmcnt(1)
	v_mfma_f32_32x32x16_bf16 v[16:31], v[110:113], v[58:61], v[16:31]
	v_lshlrev_b64 v[44:45], 12, v[132:133]
	v_lshl_add_u64 v[100:101], s[0:1], 0, v[46:47]
	s_waitcnt vmcnt(8)
	v_lshlrev_b32_e32 v58, 16, v135
	v_lshl_add_u64 v[46:47], v[62:63], 0, v[44:45]
	v_mov_b32_e32 v59, v49
	v_lshlrev_b64 v[60:61], 12, v[124:125]
	s_waitcnt vmcnt(5)
	s_nop 3
	v_add_f32_e32 v16, v16, v32
	v_mul_f32_e32 v16, v16, v58
	v_cvt_pk_bf16_f32 v16, v16, s0
	v_or_b32_e32 v58, 16, v48
	global_store_short v[46:47], v16, off offset:2048
	v_mad_u64_u32 v[46:47], s[6:7], v100, s64, v[54:55]
	v_lshl_add_u64 v[102:103], s[0:1], 0, v[58:59]
	v_mad_i32_i24 v47, v101, s64, v47
	v_mad_u64_u32 v[58:59], s[6:7], v102, s64, v[54:55]
	s_waitcnt lgkmcnt(0)
	v_mfma_f32_32x32x16_bf16 v[0:15], v[110:113], v[80:83], v[0:15]
	v_lshl_add_u64 v[80:81], v[46:47], 0, s[26:27]
	v_mad_i32_i24 v59, v103, s64, v59
	v_lshl_add_u64 v[46:47], v[80:81], 0, v[56:57]
	v_lshl_add_u64 v[82:83], v[58:59], 0, s[26:27]
	v_lshl_add_u64 v[58:59], v[82:83], 0, v[56:57]
	global_load_ushort v129, v[46:47], off offset:2176
	global_load_ushort v130, v[58:59], off offset:2176
	v_lshlrev_b32_e32 v16, 16, v128
	v_add_f32_e32 v17, v17, v33
	v_mul_f32_e32 v16, v17, v16
	v_cvt_pk_bf16_f32 v46, v16, s0
	v_lshl_add_u64 v[16:17], v[62:63], 0, v[64:65]
	global_store_short v[16:17], v46, off offset:2048
	s_waitcnt vmcnt(8)
	v_lshlrev_b32_e32 v16, 16, v106
	v_add_f32_e32 v17, v18, v34
	v_mul_f32_e32 v16, v17, v16
	v_lshlrev_b64 v[46:47], 12, v[84:85]
	v_cvt_pk_bf16_f32 v18, v16, s0
	v_lshl_add_u64 v[16:17], v[62:63], 0, v[46:47]
	global_store_short v[16:17], v18, off offset:2048
	s_waitcnt vmcnt(8)
	v_lshlrev_b32_e32 v16, 16, v107
	v_add_f32_e32 v17, v19, v35
	v_mul_f32_e32 v16, v17, v16
	v_lshlrev_b64 v[58:59], 12, v[122:123]
	v_cvt_pk_bf16_f32 v18, v16, s0
	v_lshl_add_u64 v[16:17], v[62:63], 0, v[58:59]
	global_store_short v[16:17], v18, off offset:2048
	v_lshlrev_b32_e32 v16, 16, v108
	s_waitcnt vmcnt(8)
	v_add_f32_e32 v17, v20, v36
	v_mul_f32_e32 v16, v17, v16
	v_cvt_pk_bf16_f32 v18, v16, s0
	v_lshl_add_u64 v[16:17], v[62:63], 0, v[60:61]
	global_store_short v[16:17], v18, off offset:2048
	s_waitcnt vmcnt(8)
	v_lshlrev_b32_e32 v16, 16, v104
	v_add_f32_e32 v17, v21, v37
	v_mul_f32_e32 v16, v17, v16
	v_lshlrev_b64 v[20:21], 12, v[126:127]
	v_cvt_pk_bf16_f32 v112, v16, s0
	v_lshl_add_u64 v[42:43], v[62:63], 0, v[20:21]
	v_or_b32_e32 v84, 17, v48
	v_mov_b32_e32 v85, v49
	global_store_short v[42:43], v112, off offset:2048
	v_or_b32_e32 v42, 19, v48
	v_mov_b32_e32 v43, v49
	v_lshl_add_u64 v[104:105], s[0:1], 0, v[84:85]
	v_lshl_add_u64 v[112:113], s[0:1], 0, v[42:43]
	v_mad_u64_u32 v[84:85], s[6:7], v104, s64, v[54:55]
	v_mad_u64_u32 v[42:43], s[6:7], v112, s64, v[54:55]
	v_mad_i32_i24 v85, v105, s64, v85
	v_mad_i32_i24 v43, v113, s64, v43
	global_load_dwordx4 v[16:19], v[40:41], off offset:64
	v_lshl_add_u64 v[106:107], v[84:85], 0, s[26:27]
	v_lshl_add_u64 v[114:115], v[42:43], 0, s[26:27]
	v_lshl_add_u64 v[84:85], v[106:107], 0, v[56:57]
	v_lshl_add_u64 v[42:43], v[114:115], 0, v[56:57]
	global_load_ushort v128, v[84:85], off offset:2176
	global_load_ushort v132, v[42:43], off offset:2176
	v_or_b32_e32 v84, 18, v48
	v_mov_b32_e32 v85, v49
	v_lshl_add_u64 v[108:109], s[0:1], 0, v[84:85]
	v_mad_u64_u32 v[84:85], s[6:7], v108, s64, v[54:55]
	v_mad_i32_i24 v85, v109, s64, v85
	v_lshl_add_u64 v[110:111], v[84:85], 0, s[26:27]
	v_lshl_add_u64 v[84:85], v[110:111], 0, v[56:57]
	global_load_ushort v131, v[84:85], off offset:2176
	v_or_b32_e32 v42, 24, v48
	v_mov_b32_e32 v43, v49
	v_lshl_add_u64 v[116:117], s[0:1], 0, v[42:43]
	v_mad_u64_u32 v[42:43], s[6:7], v116, s64, v[54:55]
	v_or_b32_e32 v84, 25, v48
	v_mov_b32_e32 v85, v49
	v_mad_i32_i24 v43, v117, s64, v43
	v_lshl_add_u64 v[120:121], s[0:1], 0, v[84:85]
	v_lshl_add_u64 v[118:119], v[42:43], 0, s[26:27]
	v_mad_u64_u32 v[84:85], s[6:7], v120, s64, v[54:55]
	v_lshl_add_u64 v[42:43], v[118:119], 0, v[56:57]
	v_mad_i32_i24 v85, v121, s64, v85
	global_load_ushort v133, v[42:43], off offset:2176
	s_nop 0
	global_load_dwordx4 v[40:43], v[40:41], off offset:96
	v_lshl_add_u64 v[122:123], v[84:85], 0, s[26:27]
	v_lshl_add_u64 v[84:85], v[122:123], 0, v[56:57]
	global_load_ushort v134, v[84:85], off offset:2176
	v_or_b32_e32 v84, 26, v48
	v_mov_b32_e32 v85, v49
	v_lshl_add_u64 v[124:125], s[0:1], 0, v[84:85]
	v_mad_u64_u32 v[84:85], s[6:7], v124, s64, v[54:55]
	v_mad_i32_i24 v85, v125, s64, v85
	v_lshl_add_u64 v[126:127], v[84:85], 0, s[26:27]
	s_waitcnt vmcnt(15)
; __device__ __forceinline__ float bf2f(bf16_t v) { return __uint_as_float((unsigned)v << 16); }
; __device__ __forceinline__ bf16_t f2bf(float f) { return (bf16_t)(pk_bf16(f, 0.f) & 0xffffu); }
; __device__ __forceinline__ int crow(int reg, int h) { return (reg & 3) + 8 * (reg >> 2) + 4 * h; }
; __device__ __forceinline__ void gmlp_unit(LAS unsigned char* lds, const bf16_t* __restrict__ Zb, const bf16_t* __restrict__ wsp, const float* __restrict__ bsp, bf16_t* __restrict__ mix, int chunk, int g) {
;     ...
; #pragma unroll
;     for (int ci = 0; ci < 2; ++ci)
; #pragma unroll
;         for (int e = 0; e < 16; ++e) {
;             const int p = 32 * pb + crow(e, h), c = 32 * (cb0 + ci) + r;
;             const float u = bf2f(Zb[(row0 + p) * NIN0 + 1088 + g * 128 + c]);
;             mix[(row0 + p) * DM + 1024 + g * 128 + c] = f2bf(u * (acc[ci][e] + bsp[g * 128 + p]));
	v_lshlrev_b32_e32 v97, 16, v97
	v_add_f32_e32 v22, v22, v38
	v_lshl_add_u64 v[84:85], v[126:127], 0, v[56:57]
	v_mul_f32_e32 v22, v22, v97
	global_load_ushort v97, v[84:85], off offset:2176
	v_lshlrev_b64 v[84:85], 12, v[98:99]
	v_cvt_pk_bf16_f32 v22, v22, s0
	v_lshl_add_u64 v[98:99], v[62:63], 0, v[84:85]
	v_or_b32_e32 v48, 27, v48
	global_store_short v[98:99], v22, off offset:2048
	v_lshl_add_u64 v[98:99], s[0:1], 0, v[48:49]
	v_mad_u64_u32 v[54:55], s[0:1], v98, s64, v[54:55]
	v_mad_i32_i24 v55, v99, s64, v55
	v_lshl_add_u64 v[54:55], v[54:55], 0, s[26:27]
	v_lshl_add_u64 v[56:57], v[54:55], 0, v[56:57]
	global_load_ushort v135, v[56:57], off offset:2176
	s_waitcnt vmcnt(16)
	v_lshlrev_b32_e32 v22, 16, v129
	v_add_f32_e32 v23, v23, v39
	v_mul_f32_e32 v22, v23, v22
	v_cvt_pk_bf16_f32 v48, v22, s0
	v_lshlrev_b64 v[22:23], 12, v[100:101]
	v_lshl_add_u64 v[56:57], v[62:63], 0, v[22:23]
	global_store_short v[56:57], v48, off offset:2048
	v_or_b32_e32 v48, s4, v53
	v_lshl_add_u64 v[56:57], v[74:75], 0, v[48:49]
	global_load_ushort v53, v[56:57], off offset:2176
	s_waitcnt vmcnt(17)
	v_lshlrev_b32_e32 v100, 16, v130
	v_lshl_add_u64 v[70:71], v[70:71], 0, v[48:49]
	v_lshl_add_u64 v[72:73], v[72:73], 0, v[48:49]
	v_lshl_add_u64 v[66:67], v[66:67], 0, v[48:49]
	v_add_f32_e32 v0, v0, v32
	v_add_f32_e32 v1, v1, v33
	v_lshl_add_u64 v[32:33], v[54:55], 0, v[48:49]
	global_load_ushort v32, v[32:33], off offset:2176
	s_waitcnt vmcnt(12)
	v_add_f32_e32 v24, v24, v16
	v_mul_f32_e32 v24, v24, v100
	global_load_ushort v100, v[70:71], off offset:2176
	v_lshlrev_b64 v[56:57], 12, v[102:103]
	v_cvt_pk_bf16_f32 v24, v24, s0
	v_lshl_add_u64 v[74:75], v[62:63], 0, v[56:57]
	global_store_short v[74:75], v24, off offset:2048
	s_waitcnt vmcnt(13)
	v_lshlrev_b32_e32 v24, 16, v128
	v_lshl_add_u64 v[74:75], v[76:77], 0, v[48:49]
	v_add_f32_e32 v25, v25, v17
	global_load_ushort v76, v[74:75], off offset:2176
	v_mul_f32_e32 v24, v25, v24
	v_cvt_pk_bf16_f32 v77, v24, s0
	v_lshlrev_b64 v[24:25], 12, v[104:105]
	v_lshl_add_u64 v[74:75], v[62:63], 0, v[24:25]
	global_store_short v[74:75], v77, off offset:2048
	global_load_ushort v77, v[72:73], off offset:2176
	s_waitcnt vmcnt(14)
	v_lshlrev_b32_e32 v74, 16, v131
	v_add_f32_e32 v26, v26, v18
	v_mul_f32_e32 v26, v26, v74
	global_load_ushort v102, v[66:67], off offset:2176
	v_lshlrev_b64 v[72:73], 12, v[108:109]
	v_cvt_pk_bf16_f32 v26, v26, s0
	v_lshl_add_u64 v[74:75], v[62:63], 0, v[72:73]
	global_store_short v[74:75], v26, off offset:2048
	v_lshlrev_b32_e32 v26, 16, v132
	v_add_f32_e32 v27, v27, v19
	v_mul_f32_e32 v70, v27, v26
	v_lshl_add_u64 v[26:27], v[68:69], 0, v[48:49]
	global_load_ushort v101, v[26:27], off offset:2176
	s_waitcnt vmcnt(16)
	v_lshlrev_b32_e32 v66, 16, v133
	s_waitcnt vmcnt(15)
	v_add_f32_e32 v28, v28, v40
	v_lshlrev_b64 v[26:27], 12, v[112:113]
	v_mul_f32_e32 v28, v28, v66
	v_lshl_add_u64 v[66:67], v[78:79], 0, v[48:49]
	v_lshl_add_u64 v[74:75], v[110:111], 0, v[48:49]
	v_cvt_pk_bf16_f32 v70, v70, s0
	v_lshl_add_u64 v[68:69], v[62:63], 0, v[26:27]
	global_load_ushort v78, v[66:67], off offset:2176
	v_cvt_pk_bf16_f32 v28, v28, s0
	global_load_ushort v74, v[74:75], off offset:2176
	v_lshlrev_b64 v[66:67], 12, v[116:117]
	global_store_short v[68:69], v70, off offset:2048
	v_lshl_add_u64 v[68:69], v[62:63], 0, v[66:67]
	global_store_short v[68:69], v28, off offset:2048
	v_lshl_add_u64 v[68:69], v[80:81], 0, v[48:49]
	global_load_ushort v79, v[68:69], off offset:2176
	s_waitcnt vmcnt(19)
	v_lshlrev_b32_e32 v28, 16, v134
	v_add_f32_e32 v29, v29, v41
	v_mul_f32_e32 v28, v29, v28
	v_lshl_add_u64 v[68:69], v[82:83], 0, v[48:49]
	v_cvt_pk_bf16_f32 v70, v28, s0
	v_lshlrev_b64 v[28:29], 12, v[120:121]
	global_load_ushort v80, v[68:69], off offset:2176
	v_lshl_add_u64 v[68:69], v[62:63], 0, v[28:29]
	global_store_short v[68:69], v70, off offset:2048
	v_lshl_add_u64 v[68:69], v[106:107], 0, v[48:49]
	global_load_ushort v81, v[68:69], off offset:2176
	s_waitcnt vmcnt(21)
	v_lshlrev_b32_e32 v70, 16, v97
	v_add_f32_e32 v30, v30, v42
	v_mul_f32_e32 v30, v30, v70
	v_lshlrev_b64 v[68:69], 12, v[124:125]
	v_cvt_pk_bf16_f32 v30, v30, s0
	v_lshl_add_u64 v[70:71], v[62:63], 0, v[68:69]
	global_store_short v[70:71], v30, off offset:2048
	s_waitcnt vmcnt(20)
; __device__ __forceinline__ float bf2f(bf16_t v) { return __uint_as_float((unsigned)v << 16); }
; __device__ __forceinline__ bf16_t f2bf(float f) { return (bf16_t)(pk_bf16(f, 0.f) & 0xffffu); }
; __device__ __forceinline__ int crow(int reg, int h) { return (reg & 3) + 8 * (reg >> 2) + 4 * h; }
; __device__ __forceinline__ void gmlp_unit(LAS unsigned char* lds, const bf16_t* __restrict__ Zb, const bf16_t* __restrict__ wsp, const float* __restrict__ bsp, bf16_t* __restrict__ mix, int chunk, int g) {
;     ...
; #pragma unroll
;     for (int ci = 0; ci < 2; ++ci)
; #pragma unroll
;         for (int e = 0; e < 16; ++e) {
;             const int p = 32 * pb + crow(e, h), c = 32 * (cb0 + ci) + r;
;             const float u = bf2f(Zb[(row0 + p) * NIN0 + 1088 + g * 128 + c]);
;             mix[(row0 + p) * DM + 1024 + g * 128 + c] = f2bf(u * (acc[ci][e] + bsp[g * 128 + p]));
;         }
;     __syncthreads();
; __global__ void __launch_bounds__(512, 2) mk_fwd(Args args) {
;     ...
;         for (int j = (F.vcu + F.G - 64) % F.G; j < 1152; j += F.G) gmlp_unit(F.lds, Zb, (const bf16_t*)(ws + WS_WSP), args.in[16], MIXb, j >> 3, j & 7);
	v_lshlrev_b32_e32 v30, 16, v135
	v_add_f32_e32 v31, v31, v43
	v_mul_f32_e32 v70, v31, v30
	v_lshl_add_u64 v[30:31], v[114:115], 0, v[48:49]
	global_load_ushort v75, v[30:31], off offset:2176
	v_lshlrev_b64 v[30:31], 12, v[98:99]
	v_cvt_pk_bf16_f32 v70, v70, s0
	v_lshl_add_u64 v[62:63], v[62:63], 0, v[30:31]
	global_store_short v[62:63], v70, off offset:2048
	v_lshl_add_u64 v[62:63], v[118:119], 0, v[48:49]
	global_load_ushort v82, v[62:63], off offset:2176
	s_waitcnt vmcnt(21)
	v_lshlrev_b32_e32 v53, 16, v53
	v_lshl_add_u64 v[70:71], v[122:123], 0, v[48:49]
	v_lshl_add_u64 v[62:63], s[2:3], 0, v[48:49]
	v_mul_f32_e32 v0, v0, v53
	global_load_ushort v53, v[70:71], off offset:2176
	v_cvt_pk_bf16_f32 v0, v0, s0
	v_lshl_add_u64 v[44:45], v[62:63], 0, v[44:45]
	global_store_short v[44:45], v0, off offset:2048
	v_lshl_add_u64 v[44:45], v[126:127], 0, v[48:49]
	global_load_ushort v44, v[44:45], off offset:2176
	s_waitcnt vmcnt(20)
	v_lshlrev_b32_e32 v0, 16, v76
	v_mul_f32_e32 v0, v1, v0
	v_cvt_pk_bf16_f32 v45, v0, s0
	v_lshl_add_u64 v[0:1], v[62:63], 0, v[64:65]
	global_store_short v[0:1], v45, off offset:2048
	v_add_f32_e32 v1, v2, v34
	s_waitcnt vmcnt(19)
	v_lshlrev_b32_e32 v0, 16, v77
	v_mul_f32_e32 v0, v1, v0
	v_cvt_pk_bf16_f32 v2, v0, s0
	v_lshl_add_u64 v[0:1], v[62:63], 0, v[46:47]
	global_store_short v[0:1], v2, off offset:2048
	v_lshlrev_b32_e32 v0, 16, v100
	v_add_f32_e32 v1, v3, v35
	v_mul_f32_e32 v0, v1, v0
	v_cvt_pk_bf16_f32 v2, v0, s0
	v_lshl_add_u64 v[0:1], v[62:63], 0, v[58:59]
	global_store_short v[0:1], v2, off offset:2048
	v_add_f32_e32 v1, v4, v36
	s_waitcnt vmcnt(18)
	v_lshlrev_b32_e32 v0, 16, v101
	v_mul_f32_e32 v0, v1, v0
	v_cvt_pk_bf16_f32 v2, v0, s0
	v_lshl_add_u64 v[0:1], v[62:63], 0, v[60:61]
	global_store_short v[0:1], v2, off offset:2048
	v_lshlrev_b32_e32 v0, 16, v102
	v_add_f32_e32 v1, v5, v37
	v_mul_f32_e32 v0, v1, v0
	v_cvt_pk_bf16_f32 v2, v0, s0
	v_lshl_add_u64 v[0:1], v[62:63], 0, v[20:21]
	global_store_short v[0:1], v2, off offset:2048
	s_waitcnt vmcnt(19)
	v_lshlrev_b32_e32 v0, 16, v78
	v_add_f32_e32 v1, v6, v38
	v_mul_f32_e32 v0, v1, v0
	v_cvt_pk_bf16_f32 v2, v0, s0
	v_lshl_add_u64 v[0:1], v[62:63], 0, v[84:85]
	global_store_short v[0:1], v2, off offset:2048
	s_waitcnt vmcnt(16)
	v_lshlrev_b32_e32 v0, 16, v79
	v_add_f32_e32 v1, v7, v39
	v_mul_f32_e32 v0, v1, v0
	v_cvt_pk_bf16_f32 v2, v0, s0
	v_lshl_add_u64 v[0:1], v[62:63], 0, v[22:23]
	global_store_short v[0:1], v2, off offset:2048
	v_add_f32_e32 v1, v8, v16
	s_waitcnt vmcnt(16)
	v_lshlrev_b32_e32 v0, 16, v80
	v_mul_f32_e32 v0, v1, v0
	v_cvt_pk_bf16_f32 v2, v0, s0
	v_lshl_add_u64 v[0:1], v[62:63], 0, v[56:57]
	global_store_short v[0:1], v2, off offset:2048
	s_waitcnt vmcnt(15)
	v_lshlrev_b32_e32 v0, 16, v81
	v_add_f32_e32 v1, v9, v17
	v_mul_f32_e32 v0, v1, v0
	v_cvt_pk_bf16_f32 v2, v0, s0
	v_lshl_add_u64 v[0:1], v[62:63], 0, v[24:25]
	global_store_short v[0:1], v2, off offset:2048
	v_lshlrev_b32_e32 v0, 16, v74
	v_add_f32_e32 v1, v10, v18
	v_mul_f32_e32 v0, v1, v0
	v_cvt_pk_bf16_f32 v2, v0, s0
	v_lshl_add_u64 v[0:1], v[62:63], 0, v[72:73]
	global_store_short v[0:1], v2, off offset:2048
	s_waitcnt vmcnt(15)
	v_lshlrev_b32_e32 v0, 16, v75
	v_add_f32_e32 v1, v11, v19
	v_mul_f32_e32 v0, v1, v0
	v_cvt_pk_bf16_f32 v2, v0, s0
	v_lshl_add_u64 v[0:1], v[62:63], 0, v[26:27]
	global_store_short v[0:1], v2, off offset:2048
	s_waitcnt vmcnt(14)
	v_lshlrev_b32_e32 v0, 16, v82
	v_add_f32_e32 v1, v12, v40
	v_mul_f32_e32 v0, v1, v0
	v_cvt_pk_bf16_f32 v2, v0, s0
	v_lshl_add_u64 v[0:1], v[62:63], 0, v[66:67]
	global_store_short v[0:1], v2, off offset:2048
	s_waitcnt vmcnt(14)
	v_lshlrev_b32_e32 v0, 16, v53
	v_add_f32_e32 v1, v13, v41
	v_mul_f32_e32 v0, v1, v0
	v_cvt_pk_bf16_f32 v2, v0, s0
	v_lshl_add_u64 v[0:1], v[62:63], 0, v[28:29]
	global_store_short v[0:1], v2, off offset:2048
	s_waitcnt vmcnt(13)
	v_lshlrev_b32_e32 v0, 16, v44
	v_add_f32_e32 v1, v14, v42
	v_mul_f32_e32 v0, v1, v0
	v_cvt_pk_bf16_f32 v2, v0, s0
	v_lshl_add_u64 v[0:1], v[62:63], 0, v[68:69]
	global_store_short v[0:1], v2, off offset:2048
	v_lshlrev_b32_e32 v0, 16, v32
	v_add_f32_e32 v1, v15, v43
	v_mul_f32_e32 v0, v1, v0
	v_cvt_pk_bf16_f32 v2, v0, s0
	v_lshl_add_u64 v[0:1], v[62:63], 0, v[30:31]
	global_store_short v[0:1], v2, off offset:2048
	s_barrier
	s_cbranch_scc1 .LBB0_617

; #define LAS __attribute__((address_space(3)))
; __device__ __forceinline__ int crow(int reg, int h) { return (reg & 3) + 8 * (reg >> 2) + 4 * h; }
; #define MFMA32(a, b, c) __builtin_amdgcn_mfma_f32_32x32x16_bf16((a), (b), (c), 0, 0, 0)
; template <int DQK, int DV, int MODE> ...
;     ...
;             for (int hf = 0; hf < 2; ++hf) {
;                 const int kh0 = kp0 + 32 * hf;
;                 if (band && (kh0 > qa + 31 + 128 || kh0 + 31 < qa - 128)) continue;
;                 f32x16 p;
; #pragma unroll
;                 for (int e = 0; e < 16; ++e) p[e] = 0.f;
; #pragma unroll
;                 for (int d0 = 0; d0 < DQK / 16; ++d0) {
;                     const bf16x8 k0 = *(const LAS bf16x8*)(Kb + (32 * hf + r) * KS + d0 * 32 + h * 16);
;                     p = MFMA32(k0, qf[d0], p);
;                     if ((d0 & 3) == 3) __builtin_amdgcn_sched_barrier(0);
;                 }
;                 if (band && !(kh0 >= qa + 31 - 128 && kh0 + 31 <= qa + 128)) { const int qpos = qa + r;
; #pragma unroll
;                     for (int e = 0; e < 16; ++e) { int dd = kh0 + crow(e, h) - qpos; dd = dd < 0 ? -dd : dd; if (dd > 128) p[e] = -1e30f; } }
;                 float mx = fmaxf(fmaxf(p[0], p[1]), fmaxf(p[2], p[3]));
; #pragma unroll
;                 for (int e = 4; e < 16; e += 4) mx = fmaxf(fmaxf(mx, p[e]), fmaxf(fmaxf(p[e + 1], p[e + 2]), p[e + 3]));
;                 mx = fmaxf(mx, __shfl_xor(mx, 32));
;                 if (__any(mx > m + 8.f)) {
;                     const float mn = fmaxf(m, mx), al = __builtin_amdgcn_exp2f(m - mn); l *= al; m = mn;
;                     if (h == 0) wsf[r] = al;
;                     f32x4 a4[4];
; #pragma unroll
;                     for (int g = 0; g < 4; ++g) a4[g] = *(const LAS f32x4*)(wsf + 8 * g + 4 * h);
; #pragma unroll
;                     for (int d = 0; d < DV / 32; ++d)
; #pragma unroll
;                         for (int e = 0; e < 16; ++e) o[d][e] *= a4[e >> 2][e & 3];
;                 }
.LBB0_1387:
	s_mul_i32 s6, s61, 0x5400
	s_add_i32 s6, s6, 0
	v_add_u32_e32 v32, s6, v118
	v_add_u32_e32 v130, s6, v115
	s_andn2_b64 vcc, exec, s[36:37]
	v_add_u32_e32 v132, v32, v119
	s_cbranch_vccnz .LBB0_1395
	ds_read_b128 v[134:137], v132
	ds_read_b128 v[138:141], v132 offset:32
	ds_read_b128 v[142:145], v132 offset:64
	ds_read_b128 v[146:149], v132 offset:96
	s_waitcnt lgkmcnt(3)
	v_mfma_f32_32x32x16_bf16 v[32:47], v[134:137], v[48:51], 0
	s_waitcnt lgkmcnt(2)
	v_mfma_f32_32x32x16_bf16 v[32:47], v[138:141], v[52:55], v[32:47]
	s_waitcnt lgkmcnt(1)
	v_mfma_f32_32x32x16_bf16 v[32:47], v[142:145], v[56:59], v[32:47]
	s_waitcnt lgkmcnt(0)
	v_mfma_f32_32x32x16_bf16 v[32:47], v[146:149], v[60:63], v[32:47]
	s_and_b64 vcc, exec, s[4:5]
	s_cbranch_vccnz .LBB0_1391
	s_cmp_lt_i32 s62, s55
	s_cselect_b64 s[6:7], -1, 0
	s_cmp_gt_u32 s62, s56
	s_cselect_b64 s[34:35], -1, 0
	s_or_b64 s[6:7], s[6:7], s[34:35]
	s_andn2_b64 vcc, exec, s[6:7]
	s_cbranch_vccnz .LBB0_1391
	v_add_u32_e32 v133, s59, v128
	v_subrev_u32_e32 v134, 64, v133
	v_sub_u32_e32 v135, 64, v133
	v_max_i32_e32 v134, v134, v135
	v_cmp_gt_u32_e32 vcc, s39, v134
	v_subrev_u32_e32 v134, 63, v133
	v_sub_u32_e32 v135, 63, v133
	v_max_i32_e32 v134, v134, v135
	v_cndmask_b32_e32 v32, v125, v32, vcc
	v_cmp_gt_u32_e32 vcc, s39, v134
	v_subrev_u32_e32 v134, 62, v133
	v_sub_u32_e32 v135, 62, v133
	v_max_i32_e32 v134, v134, v135
	v_cndmask_b32_e32 v33, v125, v33, vcc
	v_cmp_gt_u32_e32 vcc, s39, v134
	v_subrev_u32_e32 v134, 61, v133
	v_sub_u32_e32 v135, 61, v133
	v_max_i32_e32 v134, v134, v135
	v_cndmask_b32_e32 v34, v125, v34, vcc
	v_cmp_gt_u32_e32 vcc, s39, v134
	v_subrev_u32_e32 v134, 56, v133
	v_sub_u32_e32 v135, 56, v133
	v_max_i32_e32 v134, v134, v135
	v_cndmask_b32_e32 v35, v125, v35, vcc
	v_cmp_gt_u32_e32 vcc, s39, v134
	v_subrev_u32_e32 v134, 55, v133
	v_sub_u32_e32 v135, 55, v133
	v_max_i32_e32 v134, v134, v135
	v_cndmask_b32_e32 v36, v125, v36, vcc
	v_cmp_gt_u32_e32 vcc, s39, v134
	v_subrev_u32_e32 v134, 54, v133
	v_sub_u32_e32 v135, 54, v133
	v_max_i32_e32 v134, v134, v135
	v_cndmask_b32_e32 v37, v125, v37, vcc
	v_cmp_gt_u32_e32 vcc, s39, v134
	v_subrev_u32_e32 v134, 53, v133
	v_sub_u32_e32 v135, 53, v133
	v_max_i32_e32 v134, v134, v135
	v_cndmask_b32_e32 v38, v125, v38, vcc
	v_cmp_gt_u32_e32 vcc, s39, v134
	v_subrev_u32_e32 v134, 48, v133
	v_sub_u32_e32 v135, 48, v133
	v_max_i32_e32 v134, v134, v135
	v_cndmask_b32_e32 v39, v125, v39, vcc
	v_cmp_gt_u32_e32 vcc, s39, v134
	v_subrev_u32_e32 v134, 47, v133
	v_sub_u32_e32 v135, 47, v133
	v_max_i32_e32 v134, v134, v135
	v_cndmask_b32_e32 v40, v125, v40, vcc
	v_cmp_gt_u32_e32 vcc, s39, v134
	v_subrev_u32_e32 v134, 46, v133
	v_sub_u32_e32 v135, 46, v133
	v_max_i32_e32 v134, v134, v135
	v_cndmask_b32_e32 v41, v125, v41, vcc
	v_cmp_gt_u32_e32 vcc, s39, v134
	v_subrev_u32_e32 v134, 45, v133
	v_sub_u32_e32 v135, 45, v133
	v_max_i32_e32 v134, v134, v135
	v_cndmask_b32_e32 v42, v125, v42, vcc
	v_cmp_gt_u32_e32 vcc, s39, v134
	v_subrev_u32_e32 v134, 40, v133
	v_sub_u32_e32 v135, 40, v133
	v_max_i32_e32 v134, v134, v135
	v_cndmask_b32_e32 v43, v125, v43, vcc
	v_cmp_gt_u32_e32 vcc, s39, v134
	v_subrev_u32_e32 v134, 39, v133
	v_sub_u32_e32 v135, 39, v133
	v_max_i32_e32 v134, v134, v135
	v_cndmask_b32_e32 v44, v125, v44, vcc
	v_cmp_gt_u32_e32 vcc, s39, v134
	v_subrev_u32_e32 v134, 38, v133
	v_sub_u32_e32 v135, 38, v133
	v_max_i32_e32 v134, v134, v135
	v_cndmask_b32_e32 v45, v125, v45, vcc
	v_cmp_gt_u32_e32 vcc, s39, v134
	v_subrev_u32_e32 v134, 37, v133
	v_sub_u32_e32 v133, 37, v133
	v_max_i32_e32 v133, v134, v133
	v_cndmask_b32_e32 v46, v125, v46, vcc
	v_cmp_gt_u32_e32 vcc, s39, v133
	s_nop 1
	v_cndmask_b32_e32 v47, v125, v47, vcc
.LBB0_1391:
	s_nop 9
	v_max_f32_e32 v133, v35, v35
	v_max_f32_e32 v134, v34, v34
	v_max_f32_e32 v133, v134, v133
	v_max3_f32 v133, v32, v33, v133
	v_max3_f32 v134, v37, v38, v39
	v_max3_f32 v133, v133, v36, v134
	v_max3_f32 v134, v41, v42, v43
	v_max3_f32 v133, v133, v40, v134
	v_max3_f32 v134, v45, v46, v47
	v_max3_f32 v133, v133, v44, v134
	v_mov_b32_e32 v134, v133
	s_nop 1
	v_permlane32_swap_b32_e32 v133, v134
	v_max_f32_e32 v134, v134, v134
	v_max_f32_e32 v133, v133, v134
	v_add_f32_e32 v134, 0x41000000, v131
	v_cmp_gt_f32_e32 vcc, v133, v134
	s_cbranch_vccz .LBB0_1396
	v_max_f32_e32 v133, v133, v133
	v_max_f32_e32 v134, v131, v131
	v_max_f32_e32 v133, v134, v133
	v_sub_f32_e32 v131, v131, v133
	v_exp_f32_e32 v131, v131
	s_and_saveexec_b64 s[36:37], s[2:3]
	ds_write_b32 v127, v131 offset:43008
	s_or_b64 exec, exec, s[36:37]
	ds_read_b128 v[134:137], v126 offset:43104
	ds_read_b128 v[138:141], v126 offset:43072
	ds_read_b128 v[142:145], v126 offset:43040
	ds_read_b128 v[146:149], v126 offset:43008
	v_mul_f32_e32 v129, v129, v131
	s_waitcnt lgkmcnt(3)
	v_pk_mul_f32 v[14:15], v[14:15], v[136:137]
	s_waitcnt lgkmcnt(2)
	v_pk_mul_f32 v[10:11], v[10:11], v[140:141]
	s_waitcnt lgkmcnt(1)
	v_pk_mul_f32 v[6:7], v[6:7], v[144:145]
	s_waitcnt lgkmcnt(0)
	v_pk_mul_f32 v[2:3], v[2:3], v[148:149]
	v_pk_mul_f32 v[30:31], v[30:31], v[136:137]
	v_pk_mul_f32 v[26:27], v[26:27], v[140:141]
	v_pk_mul_f32 v[22:23], v[22:23], v[144:145]
	v_pk_mul_f32 v[18:19], v[18:19], v[148:149]
	v_pk_mul_f32 v[12:13], v[12:13], v[134:135]
	v_pk_mul_f32 v[8:9], v[8:9], v[138:139]
	v_pk_mul_f32 v[4:5], v[4:5], v[142:143]
	v_pk_mul_f32 v[0:1], v[0:1], v[146:147]
	v_pk_mul_f32 v[28:29], v[28:29], v[134:135]
	v_pk_mul_f32 v[24:25], v[24:25], v[138:139]
	v_pk_mul_f32 v[20:21], v[20:21], v[142:143]
	v_pk_mul_f32 v[16:17], v[16:17], v[146:147]
	s_branch .LBB0_1397

; #define LAS __attribute__((address_space(3)))
; __device__ __forceinline__ unsigned pk_bf16(float lo, float hi) { f32x2 v = {lo, hi}; bf16x2_t b = __builtin_convertvector(v, bf16x2_t); return __builtin_bit_cast(unsigned, b); }
; #define MFMA32(a, b, c) __builtin_amdgcn_mfma_f32_32x32x16_bf16((a), (b), (c), 0, 0, 0)
; template <int DQK, int DV, int MODE> ...
;     ...
;                 float ls = 0.f;
; #pragma unroll
;                 for (int e = 0; e < 16; ++e) { p[e] = __builtin_amdgcn_exp2f(p[e] - m); ls += p[e]; }
;                 l += ls;
;                 bf16x8 pa[2];
; #pragma unroll
;                 for (int ks = 0; ks < 2; ++ks) { u32x4 w;
; #pragma unroll
;                     for (int j = 0; j < 4; ++j) { const int e = 8 * ks + 2 * j; w[j] = pk_bf16(p[e], p[e + 1]); }
;                     pa[ks] = __builtin_bit_cast(bf16x8, w); }
; #pragma unroll
;                 for (int d = 0; d < DV / 32; ++d)
; #pragma unroll
;                     for (int ks = 0; ks < 2; ++ks) {
;                         const LAS unsigned char* vp = Vb + vlane + (32 * hf + 16 * ks) * VS + d * 64;
;                         const s16x4 lo = tr_read(vp), hi = tr_read(vp + 8 * VS);
;                         const bf16x8 vf = __builtin_shufflevector(lo, hi, 0, 1, 2, 3, 4, 5, 6, 7);
;                         o[d] = MFMA32(pa[ks], vf, o[d]);
;                         if (ks == 1 && (d & 1) == 1) __builtin_amdgcn_sched_barrier(0);
;                     }
;                 __builtin_amdgcn_sched_barrier(0);
.LBB0_1397:
	v_add_u32_e32 v166, v130, v116
	ds_read_b64_tr_b16 v[168:169], v166 offset:9216
	ds_read_b64_tr_b16 v[170:171], v166 offset:10752
	ds_read_b64_tr_b16 v[172:173], v166 offset:9280
	ds_read_b64_tr_b16 v[174:175], v166 offset:10816
	ds_read_b64_tr_b16 v[176:177], v166 offset:12288
	ds_read_b64_tr_b16 v[178:179], v166 offset:13824
	ds_read_b64_tr_b16 v[180:181], v166 offset:12352
	ds_read_b64_tr_b16 v[182:183], v166 offset:13888
	v_sub_f32_e32 v32, v32, v133
	v_exp_f32_e32 v131, v32
	v_sub_f32_e32 v32, v33, v133
	v_exp_f32_e32 v134, v32
	v_sub_f32_e32 v32, v34, v133
	v_exp_f32_e32 v138, v32
	v_sub_f32_e32 v32, v35, v133
	v_exp_f32_e32 v139, v32
	v_sub_f32_e32 v32, v36, v133
	v_exp_f32_e32 v140, v32
	v_sub_f32_e32 v32, v37, v133
	v_exp_f32_e32 v141, v32
	v_sub_f32_e32 v32, v38, v133
	v_exp_f32_e32 v142, v32
	v_sub_f32_e32 v32, v39, v133
	v_exp_f32_e32 v143, v32
	v_sub_f32_e32 v32, v40, v133
	v_exp_f32_e32 v144, v32
	v_sub_f32_e32 v32, v41, v133
	v_exp_f32_e32 v145, v32
	v_sub_f32_e32 v32, v42, v133
	v_exp_f32_e32 v146, v32
	v_sub_f32_e32 v32, v43, v133
	v_exp_f32_e32 v147, v32
	v_sub_f32_e32 v32, v44, v133
	v_exp_f32_e32 v148, v32
	v_sub_f32_e32 v32, v45, v133
	v_exp_f32_e32 v149, v32
	v_sub_f32_e32 v32, v46, v133
	v_exp_f32_e32 v150, v32
	v_cvt_pk_bf16_f32 v32, v131, v134
	v_cvt_pk_bf16_f32 v33, v138, v139
	v_cvt_pk_bf16_f32 v34, v140, v141
	v_cvt_pk_bf16_f32 v35, v142, v143
	v_sub_f32_e32 v40, v47, v133
	v_exp_f32_e32 v151, v40
	s_waitcnt lgkmcnt(0)
	v_mfma_f32_32x32x16_bf16 v[16:31], v[32:35], v[168:171], v[16:31]
	v_cvt_pk_bf16_f32 v36, v144, v145
	v_cvt_pk_bf16_f32 v37, v146, v147
	v_cvt_pk_bf16_f32 v38, v148, v149
	v_cvt_pk_bf16_f32 v39, v150, v151
	v_add_f32_e32 v131, 0, v131
	v_add_f32_e32 v131, v134, v131
	v_mfma_f32_32x32x16_bf16 v[0:15], v[32:35], v[172:175], v[0:15]
	v_mfma_f32_32x32x16_bf16 v[16:31], v[36:39], v[176:179], v[16:31]
	v_add_f32_e32 v44, v138, v131
	v_add_f32_e32 v44, v139, v44
	v_add_f32_e32 v44, v140, v44
	v_add_f32_e32 v44, v141, v44
	v_add_f32_e32 v44, v142, v44
	v_add_f32_e32 v44, v143, v44
	v_add_f32_e32 v44, v144, v44
	v_mfma_f32_32x32x16_bf16 v[0:15], v[36:39], v[180:183], v[0:15]
	v_add_f32_e32 v32, v145, v44
	v_add_f32_e32 v32, v146, v32
	v_add_f32_e32 v32, v147, v32
	v_add_f32_e32 v32, v148, v32
	v_add_f32_e32 v32, v149, v32
	v_add_f32_e32 v32, v150, v32
	v_add_f32_e32 v32, v151, v32
	v_add_f32_e32 v129, v129, v32
	s_and_b64 vcc, exec, s[4:5]
	s_sub_i32 s36, s9, 32
	s_cbranch_vccnz .LBB0_1399

; #define LAS __attribute__((address_space(3)))
; __device__ __forceinline__ int crow(int reg, int h) { return (reg & 3) + 8 * (reg >> 2) + 4 * h; }
; #define MFMA32(a, b, c) __builtin_amdgcn_mfma_f32_32x32x16_bf16((a), (b), (c), 0, 0, 0)
; template <int DQK, int DV, int MODE> ...
;     ...
;             for (int hf = 0; hf < 2; ++hf) {
;                 const int kh0 = kp0 + 32 * hf;
;                 if (band && (kh0 > qa + 31 + 128 || kh0 + 31 < qa - 128)) continue;
;                 f32x16 p;
; #pragma unroll
;                 for (int e = 0; e < 16; ++e) p[e] = 0.f;
; #pragma unroll
;                 for (int d0 = 0; d0 < DQK / 16; ++d0) {
;                     const bf16x8 k0 = *(const LAS bf16x8*)(Kb + (32 * hf + r) * KS + d0 * 32 + h * 16);
;                     p = MFMA32(k0, qf[d0], p);
;                     if ((d0 & 3) == 3) __builtin_amdgcn_sched_barrier(0);
;                 }
;                 if (band && !(kh0 >= qa + 31 - 128 && kh0 + 31 <= qa + 128)) { const int qpos = qa + r;
; #pragma unroll
;                     for (int e = 0; e < 16; ++e) { int dd = kh0 + crow(e, h) - qpos; dd = dd < 0 ? -dd : dd; if (dd > 128) p[e] = -1e30f; } }
;                 float mx = fmaxf(fmaxf(p[0], p[1]), fmaxf(p[2], p[3]));
; #pragma unroll
;                 for (int e = 4; e < 16; e += 4) mx = fmaxf(fmaxf(mx, p[e]), fmaxf(fmaxf(p[e + 1], p[e + 2]), p[e + 3]));
;                 mx = fmaxf(mx, __shfl_xor(mx, 32));
;                 if (__any(mx > m + 8.f)) {
;                     const float mn = fmaxf(m, mx), al = __builtin_amdgcn_exp2f(m - mn); l *= al; m = mn;
;                     if (h == 0) wsf[r] = al;
;                     f32x4 a4[4];
; #pragma unroll
;                     for (int g = 0; g < 4; ++g) a4[g] = *(const LAS f32x4*)(wsf + 8 * g + 4 * h);
; #pragma unroll
;                     for (int d = 0; d < DV / 32; ++d)
; #pragma unroll
;                         for (int e = 0; e < 16; ++e) o[d][e] *= a4[e >> 2][e & 3];
;                 }
.LBB0_1399:
	s_andn2_b64 vcc, exec, s[26:27]
	s_cbranch_vccnz .LBB0_1407
	ds_read_b128 v[134:137], v132 offset:4608
	ds_read_b128 v[138:141], v132 offset:4640
	ds_read_b128 v[142:145], v132 offset:4672
	ds_read_b128 v[146:149], v132 offset:4704
	s_waitcnt lgkmcnt(3)
	v_mfma_f32_32x32x16_bf16 v[32:47], v[134:137], v[48:51], 0
	s_waitcnt lgkmcnt(2)
	v_mfma_f32_32x32x16_bf16 v[32:47], v[138:141], v[52:55], v[32:47]
	s_waitcnt lgkmcnt(1)
	v_mfma_f32_32x32x16_bf16 v[32:47], v[142:145], v[56:59], v[32:47]
	s_waitcnt lgkmcnt(0)
	v_mfma_f32_32x32x16_bf16 v[32:47], v[146:149], v[60:63], v[32:47]
	s_and_b64 vcc, exec, s[4:5]
	s_cbranch_vccnz .LBB0_1403
	s_cmp_lt_i32 s36, s55
	s_cselect_b64 s[4:5], -1, 0
	s_cmp_gt_u32 s36, s56
	s_cselect_b64 s[6:7], -1, 0
	s_or_b64 s[4:5], s[4:5], s[6:7]
	s_andn2_b64 vcc, exec, s[4:5]
	s_cbranch_vccnz .LBB0_1403
	v_add_u32_e32 v131, s59, v128
	v_subrev_u32_e32 v132, 32, v131
	v_sub_u32_e32 v134, 32, v131
	v_max_i32_e32 v132, v132, v134
	v_cmp_gt_u32_e32 vcc, s39, v132
	v_subrev_u32_e32 v132, 31, v131
	v_sub_u32_e32 v134, 31, v131
	v_max_i32_e32 v132, v132, v134
	v_cndmask_b32_e32 v32, v125, v32, vcc
	v_cmp_gt_u32_e32 vcc, s39, v132
	v_subrev_u32_e32 v132, 30, v131
	v_sub_u32_e32 v134, 30, v131
	v_max_i32_e32 v132, v132, v134
	v_cndmask_b32_e32 v33, v125, v33, vcc
	v_cmp_gt_u32_e32 vcc, s39, v132
	v_subrev_u32_e32 v132, 29, v131
	v_sub_u32_e32 v134, 29, v131
	v_max_i32_e32 v132, v132, v134
	v_cndmask_b32_e32 v34, v125, v34, vcc
	v_cmp_gt_u32_e32 vcc, s39, v132
	v_subrev_u32_e32 v132, 24, v131
	v_sub_u32_e32 v134, 24, v131
	v_max_i32_e32 v132, v132, v134
	v_cndmask_b32_e32 v35, v125, v35, vcc
	v_cmp_gt_u32_e32 vcc, s39, v132
	v_subrev_u32_e32 v132, 23, v131
	v_sub_u32_e32 v134, 23, v131
	v_max_i32_e32 v132, v132, v134
	v_cndmask_b32_e32 v36, v125, v36, vcc
	v_cmp_gt_u32_e32 vcc, s39, v132
	v_subrev_u32_e32 v132, 22, v131
	v_sub_u32_e32 v134, 22, v131
	v_max_i32_e32 v132, v132, v134
	v_cndmask_b32_e32 v37, v125, v37, vcc
	v_cmp_gt_u32_e32 vcc, s39, v132
	v_subrev_u32_e32 v132, 21, v131
	v_sub_u32_e32 v134, 21, v131
	v_max_i32_e32 v132, v132, v134
	v_cndmask_b32_e32 v38, v125, v38, vcc
	v_cmp_gt_u32_e32 vcc, s39, v132
	v_add_u32_e32 v132, -16, v131
	v_sub_u32_e32 v134, 16, v131
	v_max_i32_e32 v132, v132, v134
	v_cndmask_b32_e32 v39, v125, v39, vcc
	v_cmp_gt_u32_e32 vcc, s39, v132
	v_add_u32_e32 v132, -15, v131
	v_sub_u32_e32 v134, 15, v131
	v_max_i32_e32 v132, v132, v134
	v_cndmask_b32_e32 v40, v125, v40, vcc
	v_cmp_gt_u32_e32 vcc, s39, v132
	v_add_u32_e32 v132, -14, v131
	v_sub_u32_e32 v134, 14, v131
	v_max_i32_e32 v132, v132, v134
	v_cndmask_b32_e32 v41, v125, v41, vcc
	v_cmp_gt_u32_e32 vcc, s39, v132
	v_add_u32_e32 v132, -13, v131
	v_sub_u32_e32 v134, 13, v131
	v_max_i32_e32 v132, v132, v134
	v_cndmask_b32_e32 v42, v125, v42, vcc
	v_cmp_gt_u32_e32 vcc, s39, v132
	v_add_u32_e32 v132, -8, v131
	v_sub_u32_e32 v134, 8, v131
	v_max_i32_e32 v132, v132, v134
	v_cndmask_b32_e32 v43, v125, v43, vcc
	v_cmp_gt_u32_e32 vcc, s39, v132
	v_add_u32_e32 v132, -7, v131
	v_sub_u32_e32 v134, 7, v131
	v_max_i32_e32 v132, v132, v134
	v_cndmask_b32_e32 v44, v125, v44, vcc
	v_cmp_gt_u32_e32 vcc, s39, v132
	v_add_u32_e32 v132, -6, v131
	v_sub_u32_e32 v134, 6, v131
	v_max_i32_e32 v132, v132, v134
	v_cndmask_b32_e32 v45, v125, v45, vcc
	v_cmp_gt_u32_e32 vcc, s39, v132
	v_add_u32_e32 v132, -5, v131
	v_sub_u32_e32 v131, 5, v131
	v_max_i32_e32 v131, v132, v131
	v_cndmask_b32_e32 v46, v125, v46, vcc
	v_cmp_gt_u32_e32 vcc, s39, v131
	s_nop 1
	v_cndmask_b32_e32 v47, v125, v47, vcc
.LBB0_1403:
	s_nop 9
	v_max_f32_e32 v131, v35, v35
	v_max_f32_e32 v132, v34, v34
	v_max_f32_e32 v131, v132, v131
	v_max3_f32 v131, v32, v33, v131
	v_max3_f32 v132, v37, v38, v39
	v_max3_f32 v131, v131, v36, v132
	v_max3_f32 v132, v41, v42, v43
	v_max3_f32 v131, v131, v40, v132
	v_max3_f32 v132, v45, v46, v47
	v_max3_f32 v131, v131, v44, v132
	v_mov_b32_e32 v132, v131
	s_nop 1
	v_permlane32_swap_b32_e32 v131, v132
	v_max_f32_e32 v132, v132, v132
	v_max_f32_e32 v131, v131, v132
	v_add_f32_e32 v132, 0x41000000, v133
	v_cmp_gt_f32_e32 vcc, v131, v132
	s_cbranch_vccz .LBB0_1408
	v_max_f32_e32 v131, v131, v131
	v_max_f32_e32 v132, v133, v133
	v_max_f32_e32 v131, v132, v131
	v_sub_f32_e32 v132, v133, v131
	v_exp_f32_e32 v132, v132
	s_and_saveexec_b64 s[4:5], s[2:3]
	ds_write_b32 v127, v132 offset:43008
	s_or_b64 exec, exec, s[4:5]
	ds_read_b128 v[134:137], v126 offset:43104
	ds_read_b128 v[138:141], v126 offset:43072
	ds_read_b128 v[142:145], v126 offset:43040
	ds_read_b128 v[146:149], v126 offset:43008
	v_mul_f32_e32 v129, v129, v132
	s_waitcnt lgkmcnt(3)
	v_pk_mul_f32 v[14:15], v[14:15], v[136:137]
	s_waitcnt lgkmcnt(2)
	v_pk_mul_f32 v[10:11], v[10:11], v[140:141]
	s_waitcnt lgkmcnt(1)
	v_pk_mul_f32 v[6:7], v[6:7], v[144:145]
	s_waitcnt lgkmcnt(0)
	v_pk_mul_f32 v[2:3], v[2:3], v[148:149]
	v_pk_mul_f32 v[30:31], v[30:31], v[136:137]
	v_pk_mul_f32 v[26:27], v[26:27], v[140:141]
	v_pk_mul_f32 v[22:23], v[22:23], v[144:145]
	v_pk_mul_f32 v[18:19], v[18:19], v[148:149]
	v_pk_mul_f32 v[12:13], v[12:13], v[134:135]
	v_pk_mul_f32 v[8:9], v[8:9], v[138:139]
	v_pk_mul_f32 v[4:5], v[4:5], v[142:143]
	v_pk_mul_f32 v[0:1], v[0:1], v[146:147]
	v_pk_mul_f32 v[28:29], v[28:29], v[134:135]
	v_pk_mul_f32 v[24:25], v[24:25], v[138:139]
	v_pk_mul_f32 v[20:21], v[20:21], v[142:143]
	v_pk_mul_f32 v[16:17], v[16:17], v[146:147]
	s_branch .LBB0_1409

; #define LAS __attribute__((address_space(3)))
; __device__ __forceinline__ unsigned pk_bf16(float lo, float hi) { f32x2 v = {lo, hi}; bf16x2_t b = __builtin_convertvector(v, bf16x2_t); return __builtin_bit_cast(unsigned, b); }
; #define MFMA32(a, b, c) __builtin_amdgcn_mfma_f32_32x32x16_bf16((a), (b), (c), 0, 0, 0)
; template <int DQK, int DV, int MODE> ...
;     ...
;                 float ls = 0.f;
; #pragma unroll
;                 for (int e = 0; e < 16; ++e) { p[e] = __builtin_amdgcn_exp2f(p[e] - m); ls += p[e]; }
;                 l += ls;
;                 bf16x8 pa[2];
; #pragma unroll
;                 for (int ks = 0; ks < 2; ++ks) { u32x4 w;
; #pragma unroll
;                     for (int j = 0; j < 4; ++j) { const int e = 8 * ks + 2 * j; w[j] = pk_bf16(p[e], p[e + 1]); }
;                     pa[ks] = __builtin_bit_cast(bf16x8, w); }
; #pragma unroll
;                 for (int d = 0; d < DV / 32; ++d)
; #pragma unroll
;                     for (int ks = 0; ks < 2; ++ks) {
;                         const LAS unsigned char* vp = Vb + vlane + (32 * hf + 16 * ks) * VS + d * 64;
;                         const s16x4 lo = tr_read(vp), hi = tr_read(vp + 8 * VS);
;                         const bf16x8 vf = __builtin_shufflevector(lo, hi, 0, 1, 2, 3, 4, 5, 6, 7);
;                         o[d] = MFMA32(pa[ks], vf, o[d]);
;                         if (ks == 1 && (d & 1) == 1) __builtin_amdgcn_sched_barrier(0);
;                     }
;                 __builtin_amdgcn_sched_barrier(0);
;             }
.LBB0_1409:
	v_add_u32_e32 v166, v130, v116
	ds_read_b64_tr_b16 v[168:169], v166 offset:15360
	ds_read_b64_tr_b16 v[170:171], v166 offset:16896
	ds_read_b64_tr_b16 v[172:173], v166 offset:15424
	ds_read_b64_tr_b16 v[174:175], v166 offset:16960
	ds_read_b64_tr_b16 v[176:177], v166 offset:18432
	ds_read_b64_tr_b16 v[178:179], v166 offset:19968
	ds_read_b64_tr_b16 v[180:181], v166 offset:18496
	ds_read_b64_tr_b16 v[182:183], v166 offset:20032
	v_sub_f32_e32 v32, v32, v131
	v_exp_f32_e32 v132, v32
	v_sub_f32_e32 v32, v33, v131
	v_exp_f32_e32 v133, v32
	v_sub_f32_e32 v32, v34, v131
	v_exp_f32_e32 v136, v32
	v_sub_f32_e32 v32, v35, v131
	v_exp_f32_e32 v137, v32
	v_sub_f32_e32 v32, v36, v131
	v_exp_f32_e32 v138, v32
	v_sub_f32_e32 v32, v37, v131
	v_exp_f32_e32 v139, v32
	v_sub_f32_e32 v32, v38, v131
	v_exp_f32_e32 v140, v32
	v_sub_f32_e32 v32, v39, v131
	v_exp_f32_e32 v141, v32
	v_sub_f32_e32 v32, v40, v131
	v_exp_f32_e32 v142, v32
	v_sub_f32_e32 v32, v41, v131
	v_exp_f32_e32 v143, v32
	v_sub_f32_e32 v32, v42, v131
	v_exp_f32_e32 v144, v32
	v_sub_f32_e32 v32, v43, v131
	v_exp_f32_e32 v145, v32
	v_sub_f32_e32 v32, v44, v131
	v_exp_f32_e32 v146, v32
	v_sub_f32_e32 v32, v45, v131
	v_exp_f32_e32 v147, v32
	v_sub_f32_e32 v32, v46, v131
	v_exp_f32_e32 v148, v32
	v_cvt_pk_bf16_f32 v32, v132, v133
	v_cvt_pk_bf16_f32 v33, v136, v137
	v_cvt_pk_bf16_f32 v34, v138, v139
	v_cvt_pk_bf16_f32 v35, v140, v141
	v_sub_f32_e32 v40, v47, v131
	v_exp_f32_e32 v149, v40
	s_waitcnt lgkmcnt(0)
	v_mfma_f32_32x32x16_bf16 v[16:31], v[32:35], v[168:171], v[16:31]
	v_cvt_pk_bf16_f32 v36, v142, v143
	v_cvt_pk_bf16_f32 v37, v144, v145
	v_cvt_pk_bf16_f32 v38, v146, v147
	v_cvt_pk_bf16_f32 v39, v148, v149
	v_add_f32_e32 v132, 0, v132
	v_add_f32_e32 v150, v133, v132
	v_mfma_f32_32x32x16_bf16 v[0:15], v[32:35], v[172:175], v[0:15]
	v_mfma_f32_32x32x16_bf16 v[16:31], v[36:39], v[176:179], v[16:31]
	v_add_f32_e32 v44, v136, v150
	v_add_f32_e32 v44, v137, v44
	v_add_f32_e32 v44, v138, v44
	v_add_f32_e32 v44, v139, v44
	v_add_f32_e32 v44, v140, v44
	v_add_f32_e32 v44, v141, v44
	v_add_f32_e32 v44, v142, v44
	v_mfma_f32_32x32x16_bf16 v[0:15], v[36:39], v[180:183], v[0:15]
	v_add_f32_e32 v32, v143, v44
	v_add_f32_e32 v32, v144, v32
	v_add_f32_e32 v32, v145, v32
	v_add_f32_e32 v32, v146, v32
	v_add_f32_e32 v32, v147, v32
	v_add_f32_e32 v32, v148, v32
	v_add_f32_e32 v32, v149, v32
	v_add_f32_e32 v129, v129, v32
	s_andn2_b64 vcc, exec, s[24:25]
	s_cbranch_vccnz .LBB0_1377
	s_branch .LBB0_1383

; template <bool FINAL, bool XB, bool MI = false> ...
;     ...
; #pragma unroll
;         for (int u = 0; u < 2; ++u) {
;             const int row = row0 + u * NGW; if (row >= nrows) break;
;             const bool lat = row < MLAT; const int b = lat ? (row >> 11) : 8;
;             if (!lat && part) {
;                 const size_t ro = (size_t)(row - MLAT) * DM;
; #pragma unroll
;                 for (int j = 0; j < 8; ++j) { const int c = 4 * F.lane + 256 * j; const f32x4 g4 = *(const f32x4*)(pgate + c);
;                     const f32x4 p = (*(const f32x4*)(part + ro + c) + *(const f32x4*)(part + (size_t)MCTX * DM + ro + c)) + (*(const f32x4*)(part + (size_t)2 * MCTX * DM + ro + c) + *(const f32x4*)(part + (size_t)3 * MCTX * DM + ro + c));
;                     v[u][j] = v[u][j] + g4 * p; *(f32x4*)(ctx_wb + ro + c) = v[u][j]; }
;             }
; #pragma unroll
;             for (int j = 0; j < 8; ++j) ss[u] += (v[u][j][0] * v[u][j][0] + v[u][j][1] * v[u][j][1]) + (v[u][j][2] * v[u][j][2] + v[u][j][3] * v[u][j][3]);
;             const float r = 1.0f / sqrtf(wave_sum(ss[u]) * (1.0f / DM) + EPS);
; #pragma unroll
;             for (int j = 0; j < 8; ++j) {
;                 const int c = 4 * F.lane + 256 * j;
;                 const f32x4 g4 = *(const f32x4*)(gain + c);
;                 f32x4 o = v[u][j] * r * g4;
;                 if (FINAL) { *(f32x4*)(outf + (size_t)row * DM + c) = o; }
.LBB0_1772:
	s_waitcnt vmcnt(7)
	v_lshlrev_b32_e32 v138, 16, v110
	v_and_b32_e32 v139, 0xffff0000, v110
	v_lshlrev_b32_e32 v110, 16, v111
	v_and_b32_e32 v111, 0xffff0000, v111
	v_mul_f32_e32 v34, v111, v111
	s_waitcnt vmcnt(6)
	v_lshlrev_b32_e32 v141, 16, v107
	v_lshlrev_b32_e32 v140, 16, v106
	v_and_b32_e32 v107, 0xffff0000, v107
	v_and_b32_e32 v106, 0xffff0000, v106
	s_waitcnt vmcnt(4)
	v_lshlrev_b32_e32 v147, 16, v100
	v_and_b32_e32 v149, 0xffff0000, v100
	v_lshlrev_b32_e32 v150, 16, v101
	v_and_b32_e32 v151, 0xffff0000, v101
	v_pk_fma_f32 v[100:101], v[110:111], v[110:111], v[34:35] op_sel_hi:[1,1,0]
	v_mul_f32_e32 v34, v139, v139
	v_lshlrev_b32_e32 v142, 16, v102
	v_and_b32_e32 v143, 0xffff0000, v102
	v_lshlrev_b32_e32 v144, 16, v103
	v_and_b32_e32 v145, 0xffff0000, v103
	v_pk_mul_f32 v[102:103], v[106:107], v[106:107]
	v_pk_fma_f32 v[162:163], v[138:139], v[138:139], v[34:35] op_sel_hi:[1,1,0]
	v_pk_fma_f32 v[102:103], v[140:141], v[140:141], v[102:103]
	v_mov_b32_e32 v146, v162
	v_mov_b32_e32 v164, v100
	v_mov_b32_e32 v165, v147
	v_mul_f32_e32 v148, v149, v149
	v_pk_add_f32 v[100:101], v[162:163], v[100:101]
	v_pk_mul_f32 v[162:163], v[146:147], v[164:165]
	v_pk_add_f32 v[102:103], v[102:103], v[102:103] op_sel:[0,1] op_sel_hi:[1,0]
	v_mov_b32_e32 v101, v163
	v_mov_b32_e32 v103, v148
	v_mul_f32_e32 v34, v143, v143
	v_pk_add_f32 v[100:101], v[100:101], v[102:103]
	v_pk_fma_f32 v[102:103], v[142:143], v[142:143], v[34:35] op_sel_hi:[1,1,0]
	v_mul_f32_e32 v34, v145, v145
	v_mul_f32_e32 v158, v150, v150
	v_mul_f32_e32 v160, v151, v151
	v_pk_fma_f32 v[162:163], v[144:145], v[144:145], v[34:35] op_sel_hi:[1,1,0]
	v_mov_b32_e32 v103, v158
	v_mov_b32_e32 v163, v160
	s_waitcnt vmcnt(3)
	v_lshlrev_b32_e32 v153, 16, v115
	v_lshlrev_b32_e32 v152, 16, v114
	v_and_b32_e32 v115, 0xffff0000, v115
	v_and_b32_e32 v114, 0xffff0000, v114
	v_pk_add_f32 v[102:103], v[102:103], v[162:163]
	s_waitcnt vmcnt(2)
	v_lshlrev_b32_e32 v155, 16, v113
	v_pk_add_f32 v[100:101], v[100:101], v[102:103]
	v_pk_mul_f32 v[102:103], v[114:115], v[114:115]
	v_lshlrev_b32_e32 v154, 16, v112
	v_pk_fma_f32 v[102:103], v[152:153], v[152:153], v[102:103]
	v_and_b32_e32 v113, 0xffff0000, v113
	v_and_b32_e32 v112, 0xffff0000, v112
	s_waitcnt vmcnt(0)
	v_lshlrev_b32_e32 v159, 16, v104
	v_pk_add_f32 v[102:103], v[102:103], v[102:103] op_sel:[0,1] op_sel_hi:[1,0]
	v_pk_add_f32 v[100:101], v[100:101], v[100:101] op_sel:[0,1] op_sel_hi:[1,0]
	v_pk_mul_f32 v[162:163], v[112:113], v[112:113]
	v_mov_b32_e32 v158, v100
	v_mov_b32_e32 v164, v102
	v_mov_b32_e32 v165, v159
	v_and_b32_e32 v161, 0xffff0000, v104
	v_pk_fma_f32 v[162:163], v[154:155], v[154:155], v[162:163]
	v_pk_add_f32 v[100:101], v[100:101], v[102:103]
	v_pk_mul_f32 v[102:103], v[158:159], v[164:165]
	v_and_b32_e32 v157, 0xffff0000, v108
	v_mul_f32_e32 v34, v161, v161
	v_mov_b32_e32 v101, v103
	v_pk_add_f32 v[102:103], v[162:163], v[162:163] op_sel:[0,1] op_sel_hi:[1,0]
	v_lshlrev_b32_e32 v156, 16, v108
	v_lshlrev_b32_e32 v108, 16, v109
	v_and_b32_e32 v109, 0xffff0000, v109
	v_mov_b32_e32 v103, v34
	v_mul_f32_e32 v34, v157, v157
	v_lshlrev_b32_e32 v104, 16, v105
	v_and_b32_e32 v105, 0xffff0000, v105
	v_pk_add_f32 v[100:101], v[100:101], v[102:103]
	v_pk_fma_f32 v[102:103], v[156:157], v[156:157], v[34:35] op_sel_hi:[1,1,0]
	v_mul_f32_e32 v34, v109, v109
	v_mul_f32_e32 v146, v104, v104
	v_mul_f32_e32 v148, v105, v105
	v_pk_fma_f32 v[162:163], v[108:109], v[108:109], v[34:35] op_sel_hi:[1,1,0]
	v_mov_b32_e32 v103, v146
	v_mov_b32_e32 v163, v148
	v_pk_add_f32 v[102:103], v[102:103], v[162:163]
	v_mov_b32_e32 v148, v147
	v_pk_add_f32 v[100:101], v[100:101], v[102:103]
	v_mov_b32_e32 v160, v159
	v_add_f32_e32 v34, v100, v101
	ds_bpermute_b32 v100, v116, v34
	s_waitcnt lgkmcnt(0)
	v_add_f32_e32 v34, v34, v100
	ds_bpermute_b32 v100, v117, v34
	s_waitcnt lgkmcnt(0)
	v_add_f32_e32 v34, v34, v100
	ds_bpermute_b32 v100, v118, v34
	s_waitcnt lgkmcnt(0)
	v_add_f32_e32 v34, v34, v100
	ds_bpermute_b32 v100, v119, v34
	s_waitcnt lgkmcnt(0)
	v_add_f32_e32 v34, v34, v100
	ds_bpermute_b32 v100, v120, v34
	s_waitcnt lgkmcnt(0)
	v_add_f32_e32 v34, v34, v100
	ds_bpermute_b32 v100, v121, v34
	s_waitcnt lgkmcnt(0)
	v_add_f32_e32 v34, v34, v100
	v_fmamk_f32 v34, v34, 0x3a000000, v131
	v_mul_f32_e32 v100, 0x4f800000, v34
	v_cmp_gt_f32_e32 vcc, s3, v34
	s_nop 1
	v_cndmask_b32_e32 v34, v34, v100, vcc
	v_sqrt_f32_e32 v100, v34
	s_nop 0
	v_add_u32_e32 v101, -1, v100
	v_fma_f32 v102, -v101, v100, v34
	v_cmp_ge_f32_e64 s[0:1], 0, v102
	v_add_u32_e32 v102, 1, v100
	s_nop 0
	v_cndmask_b32_e64 v101, v100, v101, s[0:1]
	v_fma_f32 v100, -v102, v100, v34
	v_cmp_lt_f32_e64 s[0:1], 0, v100
	s_nop 1
	v_cndmask_b32_e64 v100, v101, v102, s[0:1]
	v_mul_f32_e32 v101, 0x37800000, v100
	v_cndmask_b32_e32 v100, v100, v101, vcc
	v_cmp_class_f32_e32 vcc, v34, v132
	s_nop 1
	v_cndmask_b32_e32 v34, v100, v34, vcc
	v_div_scale_f32 v100, s[0:1], v34, v34, 1.0
	v_rcp_f32_e32 v101, v100
	s_nop 0
	v_fma_f32 v102, -v100, v101, 1.0
	v_fmac_f32_e32 v101, v102, v101
	v_div_scale_f32 v102, vcc, 1.0, v34, 1.0
	v_mul_f32_e32 v103, v102, v101
	v_fma_f32 v146, -v100, v103, v102
	v_fmac_f32_e32 v103, v146, v101
	v_fma_f32 v100, -v100, v103, v102
	v_div_fmas_f32 v100, v100, v101, v103
	v_div_fixup_f32 v34, v100, v34, 1.0
	v_pk_mul_f32 v[100:101], v[34:35], v[138:139] op_sel_hi:[0,1]
	v_pk_mul_f32 v[102:103], v[34:35], v[110:111] op_sel_hi:[0,1]
	v_pk_mul_f32 v[102:103], v[2:3], v[102:103]
	v_pk_mul_f32 v[100:101], v[0:1], v[100:101]
	global_store_dwordx4 v[66:67], v[100:103], off offset:-4096 nt
	s_andn2_b64 vcc, exec, s[12:13]
	s_nop 0
	v_mov_b32_e32 v100, v140
	v_mov_b32_e32 v101, v106
; template <bool FINAL, bool XB, bool MI = false> ...
;     ...
; #pragma unroll
;             for (int j = 0; j < 8; ++j) {
;                 const int c = 4 * F.lane + 256 * j;
;                 const f32x4 g4 = *(const f32x4*)(gain + c);
;                 f32x4 o = v[u][j] * r * g4;
;                 if (FINAL) { *(f32x4*)(outf + (size_t)row * DM + c) = o; }
	v_mov_b32_e32 v106, v141
	v_pk_mul_f32 v[100:101], v[34:35], v[100:101] op_sel_hi:[0,1]
	v_pk_mul_f32 v[102:103], v[34:35], v[106:107] op_sel_hi:[0,1]
	v_pk_mul_f32 v[102:103], v[6:7], v[102:103]
	v_pk_mul_f32 v[100:101], v[4:5], v[100:101]
	global_store_dwordx4 v[66:67], v[100:103], off offset:-3072 nt
	s_nop 1
	v_pk_mul_f32 v[100:101], v[34:35], v[142:143] op_sel_hi:[0,1]
	v_pk_mul_f32 v[102:103], v[34:35], v[144:145] op_sel_hi:[0,1]
	v_pk_mul_f32 v[102:103], v[10:11], v[102:103]
	v_pk_mul_f32 v[100:101], v[8:9], v[100:101]
	global_store_dwordx4 v[66:67], v[100:103], off offset:-2048 nt
	s_nop 1
	v_pk_mul_f32 v[100:101], v[34:35], v[148:149] op_sel_hi:[0,1]
	v_pk_mul_f32 v[102:103], v[34:35], v[150:151] op_sel_hi:[0,1]
	v_pk_mul_f32 v[102:103], v[14:15], v[102:103]
	v_pk_mul_f32 v[100:101], v[12:13], v[100:101]
	global_store_dwordx4 v[66:67], v[100:103], off offset:-1024 nt
	s_nop 1
	v_mov_b32_e32 v100, v152
	v_mov_b32_e32 v101, v114
	v_mov_b32_e32 v114, v153
	v_pk_mul_f32 v[100:101], v[34:35], v[100:101] op_sel_hi:[0,1]
	v_pk_mul_f32 v[102:103], v[34:35], v[114:115] op_sel_hi:[0,1]
	v_pk_mul_f32 v[102:103], v[18:19], v[102:103]
	v_pk_mul_f32 v[100:101], v[16:17], v[100:101]
	global_store_dwordx4 v[66:67], v[100:103], off nt
	s_nop 1
	v_mov_b32_e32 v100, v154
	v_mov_b32_e32 v101, v112
	v_mov_b32_e32 v112, v155
	v_pk_mul_f32 v[100:101], v[34:35], v[100:101] op_sel_hi:[0,1]
	v_pk_mul_f32 v[102:103], v[34:35], v[112:113] op_sel_hi:[0,1]
	v_pk_mul_f32 v[102:103], v[102:103], v[22:23]
	v_pk_mul_f32 v[100:101], v[100:101], v[20:21]
	global_store_dwordx4 v[66:67], v[100:103], off offset:1024 nt
	s_nop 1
	v_pk_mul_f32 v[100:101], v[34:35], v[156:157] op_sel_hi:[0,1]
	v_pk_mul_f32 v[102:103], v[34:35], v[108:109] op_sel_hi:[0,1]
	v_pk_mul_f32 v[102:103], v[102:103], v[26:27]
	v_pk_mul_f32 v[100:101], v[100:101], v[24:25]
	global_store_dwordx4 v[66:67], v[100:103], off offset:2048 nt
	s_nop 1
	v_pk_mul_f32 v[100:101], v[34:35], v[160:161] op_sel_hi:[0,1]
	v_pk_mul_f32 v[102:103], v[34:35], v[104:105] op_sel_hi:[0,1]
	v_pk_mul_f32 v[102:103], v[102:103], v[30:31]
	v_pk_mul_f32 v[100:101], v[100:101], v[28:29]
	global_store_dwordx4 v[66:67], v[100:103], off offset:3072 nt
	s_cbranch_vccnz .LBB0_1769
; template <bool FINAL, bool XB, bool MI = false> ...
;     ...
; #pragma unroll
;         for (int u = 0; u < 2; ++u) {
;             const int row = row0 + u * NGW; if (row >= nrows) break;
;             const bool lat = row < MLAT; const int b = lat ? (row >> 11) : 8;
;             if (!lat && part) {
;                 const size_t ro = (size_t)(row - MLAT) * DM;
; #pragma unroll
;                 for (int j = 0; j < 8; ++j) { const int c = 4 * F.lane + 256 * j; const f32x4 g4 = *(const f32x4*)(pgate + c);
;                     const f32x4 p = (*(const f32x4*)(part + ro + c) + *(const f32x4*)(part + (size_t)MCTX * DM + ro + c)) + (*(const f32x4*)(part + (size_t)2 * MCTX * DM + ro + c) + *(const f32x4*)(part + (size_t)3 * MCTX * DM + ro + c));
;                     v[u][j] = v[u][j] + g4 * p; *(f32x4*)(ctx_wb + ro + c) = v[u][j]; }
;             }
; #pragma unroll
;             for (int j = 0; j < 8; ++j) ss[u] += (v[u][j][0] * v[u][j][0] + v[u][j][1] * v[u][j][1]) + (v[u][j][2] * v[u][j][2] + v[u][j][3] * v[u][j][3]);
;             const float r = 1.0f / sqrtf(wave_sum(ss[u]) * (1.0f / DM) + EPS);
; #pragma unroll
;             for (int j = 0; j < 8; ++j) {
;                 const int c = 4 * F.lane + 256 * j;
;                 const f32x4 g4 = *(const f32x4*)(gain + c);
;                 f32x4 o = v[u][j] * r * g4;
;                 if (FINAL) { *(f32x4*)(outf + (size_t)row * DM + c) = o; }
	s_nop 0
	v_mov_b32_e32 v102, v81
	v_mov_b32_e32 v103, v83
	v_mov_b32_e32 v100, v80
	v_mov_b32_e32 v101, v82
	v_pk_mul_f32 v[102:103], v[102:103], v[102:103]
	v_mov_b32_e32 v104, v87
	v_mov_b32_e32 v105, v85
	v_pk_fma_f32 v[100:101], v[100:101], v[100:101], v[102:103]
	v_mov_b32_e32 v102, v86
	v_mov_b32_e32 v103, v84
	v_pk_mul_f32 v[104:105], v[104:105], v[104:105]
	v_mul_f32_e32 v34, v76, v76
	v_pk_fma_f32 v[102:103], v[102:103], v[102:103], v[104:105]
	v_pk_mul_f32 v[104:105], v[78:79], v[78:79]
	v_pk_add_f32 v[100:101], v[100:101], v[102:103]
	v_pk_mul_f32 v[102:103], v[88:89], v[88:89]
	v_pk_add_f32 v[100:101], v[100:101], v[100:101] op_sel_hi:[0,1]
	v_pk_mov_b32 v[106:107], v[104:105], v[102:103] op_sel:[1,0]
	v_mov_b32_e32 v105, v103
	v_pk_add_f32 v[102:103], v[106:107], v[104:105]
	v_pk_fma_f32 v[104:105], v[76:77], v[76:77], v[34:35] op_sel_hi:[1,1,0]
	v_mul_f32_e32 v34, v90, v90
	v_pk_add_f32 v[102:103], v[102:103], v[102:103] op_sel_hi:[0,1]
	v_pk_fma_f32 v[106:107], v[90:91], v[90:91], v[34:35] op_sel_hi:[1,1,0]
	v_mul_f32_e32 v104, v74, v74
	v_mul_f32_e32 v106, v75, v75
	v_mul_f32_e32 v102, v92, v92
	v_mul_f32_e32 v100, v93, v93
	v_pk_add_f32 v[104:105], v[104:105], v[106:107]
	v_pk_add_f32 v[100:101], v[102:103], v[100:101]
	v_pk_mul_f32 v[102:103], v[94:95], v[94:95]
	v_pk_add_f32 v[100:101], v[104:105], v[100:101]
	v_pk_mul_f32 v[104:105], v[72:73], v[72:73]
	v_mul_f32_e32 v34, v70, v70
	v_pk_mov_b32 v[106:107], v[104:105], v[102:103] op_sel:[1,0]
	v_mov_b32_e32 v105, v103
	v_pk_add_f32 v[102:103], v[106:107], v[104:105]
	v_pk_fma_f32 v[104:105], v[70:71], v[70:71], v[34:35] op_sel_hi:[1,1,0]
	v_mul_f32_e32 v34, v96, v96
	v_pk_add_f32 v[100:101], v[100:101], v[100:101] op_sel_hi:[0,1]
	v_pk_add_f32 v[102:103], v[102:103], v[102:103] op_sel_hi:[0,1]
	v_pk_fma_f32 v[106:107], v[96:97], v[96:97], v[34:35] op_sel_hi:[1,1,0]
	v_mul_f32_e32 v104, v68, v68
	v_mul_f32_e32 v106, v69, v69
	v_mul_f32_e32 v102, v98, v98
	v_mul_f32_e32 v100, v99, v99
	v_pk_add_f32 v[104:105], v[104:105], v[106:107]
	v_pk_add_f32 v[100:101], v[102:103], v[100:101]
	s_ashr_i32 s9, s8, 31
	v_pk_add_f32 v[100:101], v[104:105], v[100:101]
	s_nop 0
	v_add_f32_e32 v34, v100, v101
	ds_bpermute_b32 v100, v116, v34
	s_waitcnt lgkmcnt(0)
	v_add_f32_e32 v34, v34, v100
	ds_bpermute_b32 v100, v117, v34
	s_waitcnt lgkmcnt(0)
	v_add_f32_e32 v34, v34, v100
	ds_bpermute_b32 v100, v118, v34
	s_waitcnt lgkmcnt(0)
	v_add_f32_e32 v34, v34, v100
	ds_bpermute_b32 v100, v119, v34
	s_waitcnt lgkmcnt(0)
	v_add_f32_e32 v34, v34, v100
	ds_bpermute_b32 v100, v120, v34
	s_waitcnt lgkmcnt(0)
	v_add_f32_e32 v34, v34, v100
	ds_bpermute_b32 v100, v121, v34
	s_waitcnt lgkmcnt(0)
	v_add_f32_e32 v34, v34, v100
	v_fmamk_f32 v34, v34, 0x3a000000, v131
	v_mul_f32_e32 v100, 0x4f800000, v34
	v_cmp_gt_f32_e32 vcc, s3, v34
	s_nop 1
	v_cndmask_b32_e32 v34, v34, v100, vcc
	v_sqrt_f32_e32 v100, v34
	s_nop 0
	v_add_u32_e32 v101, -1, v100
	v_fma_f32 v102, -v101, v100, v34
	v_cmp_ge_f32_e64 s[0:1], 0, v102
	v_add_u32_e32 v102, 1, v100
	s_nop 0
	v_cndmask_b32_e64 v101, v100, v101, s[0:1]
	v_fma_f32 v100, -v102, v100, v34
	v_cmp_lt_f32_e64 s[0:1], 0, v100
	s_nop 1
	v_cndmask_b32_e64 v100, v101, v102, s[0:1]
	v_mul_f32_e32 v101, 0x37800000, v100
	v_cndmask_b32_e32 v100, v100, v101, vcc
	v_cmp_class_f32_e32 vcc, v34, v132
	s_nop 1
	v_cndmask_b32_e32 v34, v100, v34, vcc
	v_div_scale_f32 v100, s[0:1], v34, v34, 1.0
	v_rcp_f32_e32 v101, v100
	s_lshl_b64 s[0:1], s[8:9], 13
	s_add_u32 s0, s48, s0
	s_addc_u32 s1, s49, s1
	v_fma_f32 v102, -v100, v101, 1.0
	v_fmac_f32_e32 v101, v102, v101
	v_div_scale_f32 v102, vcc, 1.0, v34, 1.0
	v_mul_f32_e32 v103, v102, v101
	v_fma_f32 v104, -v100, v103, v102
	v_fmac_f32_e32 v103, v104, v101
	v_fma_f32 v100, -v100, v103, v102
	v_div_fmas_f32 v100, v100, v101, v103
	v_div_fixup_f32 v34, v100, v34, 1.0
	v_pk_mul_f32 v[100:101], v[34:35], v[82:83] op_sel_hi:[0,1]
	v_pk_mul_f32 v[102:103], v[34:35], v[84:85] op_sel_hi:[0,1]
	v_pk_mul_f32 v[102:103], v[2:3], v[102:103]
	v_pk_mul_f32 v[100:101], v[0:1], v[100:101]
	global_store_dwordx4 v133, v[100:103], s[0:1] nt
	s_nop 1
	v_pk_mul_f32 v[100:101], v[34:35], v[80:81] op_sel_hi:[0,1]
	v_pk_mul_f32 v[102:103], v[34:35], v[86:87] op_sel_hi:[0,1]
	v_pk_mul_f32 v[102:103], v[6:7], v[102:103]
	v_pk_mul_f32 v[100:101], v[4:5], v[100:101]
	global_store_dwordx4 v133, v[100:103], s[0:1] offset:1024 nt
	s_nop 1
	v_pk_mul_f32 v[100:101], v[34:35], v[78:79] op_sel_hi:[0,1]
	v_pk_mul_f32 v[102:103], v[34:35], v[88:89] op_sel_hi:[0,1]
	v_pk_mul_f32 v[102:103], v[10:11], v[102:103]
	v_pk_mul_f32 v[100:101], v[8:9], v[100:101]
	global_store_dwordx4 v133, v[100:103], s[0:1] offset:2048 nt
	s_nop 1
	v_pk_mul_f32 v[100:101], v[34:35], v[76:77] op_sel_hi:[0,1]
	v_pk_mul_f32 v[102:103], v[34:35], v[90:91] op_sel_hi:[0,1]
	v_pk_mul_f32 v[102:103], v[14:15], v[102:103]
	v_pk_mul_f32 v[100:101], v[12:13], v[100:101]
	global_store_dwordx4 v133, v[100:103], s[0:1] offset:3072 nt
	s_nop 1
	v_pk_mul_f32 v[100:101], v[34:35], v[74:75] op_sel_hi:[0,1]
	v_pk_mul_f32 v[102:103], v[34:35], v[92:93] op_sel_hi:[0,1]
	v_pk_mul_f32 v[102:103], v[18:19], v[102:103]
	v_pk_mul_f32 v[100:101], v[16:17], v[100:101]
	global_store_dwordx4 v134, v[100:103], s[0:1] nt
	s_nop 1
	v_pk_mul_f32 v[100:101], v[34:35], v[72:73] op_sel_hi:[0,1]
	v_pk_mul_f32 v[102:103], v[34:35], v[94:95] op_sel_hi:[0,1]
	v_pk_mul_f32 v[102:103], v[22:23], v[102:103]
	v_pk_mul_f32 v[100:101], v[20:21], v[100:101]
	global_store_dwordx4 v135, v[100:103], s[0:1] nt
	s_nop 1
	v_pk_mul_f32 v[100:101], v[34:35], v[70:71] op_sel_hi:[0,1]
	v_pk_mul_f32 v[102:103], v[34:35], v[96:97] op_sel_hi:[0,1]
	v_pk_mul_f32 v[102:103], v[26:27], v[102:103]
	v_pk_mul_f32 v[100:101], v[24:25], v[100:101]
	global_store_dwordx4 v136, v[100:103], s[0:1] nt
	s_nop 1
	v_pk_mul_f32 v[100:101], v[34:35], v[68:69] op_sel_hi:[0,1]
	v_pk_mul_f32 v[102:103], v[34:35], v[98:99] op_sel_hi:[0,1]
	v_pk_mul_f32 v[102:103], v[30:31], v[102:103]
	v_pk_mul_f32 v[100:101], v[28:29], v[100:101]
	global_store_dwordx4 v137, v[100:103], s[0:1] nt
	s_branch .LBB0_1769
